# v33 = v31 with the late six k-tile loads also re-issued inside ks3 right behind their LDS writes (all 12 loads of tile t+2 in ks3)
# speedup vs baseline: 1.0058x; 1.0058x over previous
.LBB0_301:
	s_mul_hi_u32 s0, s55, s25
	s_mul_i32 s1, s0, s20
	s_sub_i32 s1, s55, s1
	s_add_i32 s8, s0, 1
	s_sub_i32 s12, s1, s20
	s_cmp_ge_u32 s1, s20
	s_cselect_b32 s0, s8, s0
	s_cselect_b32 s1, s12, s1
	s_add_i32 s8, s0, 1
	s_cmp_ge_u32 s1, s20
	s_cselect_b32 s0, s8, s0
	s_add_i32 s1, s0, s23
	s_mul_i32 s0, s0, s20
	s_sub_i32 s0, s55, s0
	s_add_i32 s0, s0, s19
	s_lshl_b32 s12, s1, 8
	s_lshl_b32 s8, s0, 7
	s_mov_b64 s[0:1], s[30:31]
	v_mov_b32_e32 v0, v177
	s_mov_b32 s13, s9
	v_mbcnt_lo_u32_b32 v0, -1, v0
	v_mbcnt_hi_u32_b32 v0, -1, v0
	v_add_u32_e32 v182, s33, v0
	s_lshl_b64 s[16:17], s[12:13], 11
	v_ashrrev_i32_e32 v0, 3, v182
	v_lshlrev_b32_e32 v1, 3, v182
	s_add_u32 s56, s14, s16
	v_and_b32_e32 v6, 56, v1
	v_lshlrev_b32_e32 v1, 11, v0
	s_addc_u32 s57, s15, s17
	v_lshl_or_b32 v176, v6, 1, v1
	v_mul_lo_u32 v7, v0, s21
	v_lshl_add_u64 v[0:1], s[56:57], 0, v[176:177]
	v_add_co_u32_e32 v2, vcc, s26, v0
	s_lshl_b64 s[58:59], s[8:9], 11
	s_nop 0
	v_addc_co_u32_e32 v3, vcc, 0, v1, vcc
	v_add_co_u32_e32 v4, vcc, s27, v0
	s_add_u32 s58, s30, s58
	s_nop 0
	v_addc_co_u32_e32 v5, vcc, 0, v1, vcc
	global_load_dwordx4 v[128:131], v[2:3], off
	global_load_dwordx4 v[132:135], v[4:5], off
	v_add_co_u32_e32 v2, vcc, s34, v0
	s_addc_u32 s59, s31, s59
	s_nop 0
	v_addc_co_u32_e32 v3, vcc, 0, v1, vcc
	v_add_co_u32_e32 v4, vcc, s35, v0
	v_lshl_add_u64 v[178:179], s[58:59], 0, v[176:177]
	s_nop 0
	v_addc_co_u32_e32 v5, vcc, 0, v1, vcc
	global_load_dwordx4 v[136:139], v[2:3], off
	global_load_dwordx4 v[144:147], v[4:5], off
	v_add_co_u32_e32 v2, vcc, s36, v0
	v_bfe_u32 v185, v182, 6, 1
	s_nop 0
	v_addc_co_u32_e32 v3, vcc, 0, v1, vcc
	v_add_co_u32_e32 v4, vcc, s37, v0
	v_and_b32_e32 v184, 31, v182
	s_nop 0
	v_addc_co_u32_e32 v5, vcc, 0, v1, vcc
	v_add_co_u32_e32 v0, vcc, s38, v0
	global_load_dwordx4 v[148:151], v[2:3], off
	global_load_dwordx4 v[152:155], v[4:5], off
	v_addc_co_u32_e32 v1, vcc, 0, v1, vcc
	v_add_co_u32_e32 v2, vcc, s26, v178
	global_load_dwordx4 v[164:167], v176, s[56:57]
	global_load_dwordx4 v[140:143], v176, s[58:59]
	v_addc_co_u32_e32 v3, vcc, 0, v179, vcc
	global_load_dwordx4 v[156:159], v[0:1], off
	global_load_dwordx4 v[160:163], v[2:3], off
	v_add_co_u32_e32 v0, vcc, s27, v178
	v_bfe_u32 v186, v182, 5, 1
	s_nop 0
	v_addc_co_u32_e32 v1, vcc, 0, v179, vcc
	v_add_co_u32_e32 v2, vcc, s34, v178
	s_add_u32 s16, s30, s16
	s_nop 0
	v_addc_co_u32_e32 v3, vcc, 0, v179, vcc
	global_load_dwordx4 v[168:171], v[0:1], off
	global_load_dwordx4 v[172:175], v[2:3], off
	v_and_b32_e32 v0, 0xfffff9f, v182
	v_lshl_or_b32 v2, v185, 6, v184
	v_mul_lo_u32 v3, v0, s39
	v_or_b32_e32 v0, 0x60, v182
	v_lshlrev_b32_e32 v1, 4, v186
	v_mul_lo_u32 v4, v0, s39
	v_mul_u32_u24_e32 v2, 0x90, v2
	s_addc_u32 s17, s31, s17
	v_mov_b32_e32 v0, 0
	v_add_lshl_u32 v189, v7, v6, 1
	v_lshl_add_u64 v[180:181], s[16:17], 0, v[176:177]
	s_mov_b64 s[16:17], 0
	v_add_u32_e32 v188, v1, v3
	v_add_u32_e32 v187, v1, v4
	v_add_u32_e32 v176, v1, v2
	v_mov_b32_e32 v1, v0
	v_mov_b32_e32 v2, v0
	v_mov_b32_e32 v3, v0
	v_mov_b32_e32 v4, v0
	v_mov_b32_e32 v5, v0
	v_mov_b32_e32 v6, v0
	v_mov_b32_e32 v7, v0
	v_mov_b32_e32 v8, v0
	v_mov_b32_e32 v9, v0
	v_mov_b32_e32 v10, v0
	v_mov_b32_e32 v11, v0
	v_mov_b32_e32 v12, v0
	v_mov_b32_e32 v13, v0
	v_mov_b32_e32 v14, v0
	v_mov_b32_e32 v15, v0
	v_mov_b32_e32 v16, v0
	v_mov_b32_e32 v17, v0
	v_mov_b32_e32 v18, v0
	v_mov_b32_e32 v19, v0
	v_mov_b32_e32 v20, v0
	v_mov_b32_e32 v21, v0
	v_mov_b32_e32 v22, v0
	v_mov_b32_e32 v23, v0
	v_mov_b32_e32 v24, v0
	v_mov_b32_e32 v25, v0
	v_mov_b32_e32 v26, v0
	v_mov_b32_e32 v27, v0
	v_mov_b32_e32 v28, v0
	v_mov_b32_e32 v29, v0
	v_mov_b32_e32 v30, v0
	v_mov_b32_e32 v31, v0
	v_mov_b32_e32 v32, v0
	v_mov_b32_e32 v33, v0
	v_mov_b32_e32 v34, v0
	v_mov_b32_e32 v35, v0
	v_mov_b32_e32 v36, v0
	v_mov_b32_e32 v37, v0
	v_mov_b32_e32 v38, v0
	v_mov_b32_e32 v39, v0
	v_mov_b32_e32 v40, v0
	v_mov_b32_e32 v41, v0
	v_mov_b32_e32 v42, v0
	v_mov_b32_e32 v43, v0
	v_mov_b32_e32 v44, v0
	v_mov_b32_e32 v45, v0
	v_mov_b32_e32 v46, v0
	v_mov_b32_e32 v47, v0
	v_mov_b32_e32 v48, v0
	v_mov_b32_e32 v49, v0
	v_mov_b32_e32 v50, v0
	v_mov_b32_e32 v51, v0
	v_mov_b32_e32 v52, v0
	v_mov_b32_e32 v53, v0
	v_mov_b32_e32 v54, v0
	v_mov_b32_e32 v55, v0
	v_mov_b32_e32 v56, v0
	v_mov_b32_e32 v57, v0
	v_mov_b32_e32 v58, v0
	v_mov_b32_e32 v59, v0
	v_mov_b32_e32 v60, v0
	v_mov_b32_e32 v61, v0
	v_mov_b32_e32 v62, v0
	v_mov_b32_e32 v63, v0
	v_mov_b32_e32 v64, v0
	v_mov_b32_e32 v65, v0
	v_mov_b32_e32 v66, v0
	v_mov_b32_e32 v67, v0
	v_mov_b32_e32 v68, v0
	v_mov_b32_e32 v69, v0
	v_mov_b32_e32 v70, v0
	v_mov_b32_e32 v71, v0
	v_mov_b32_e32 v72, v0
	v_mov_b32_e32 v73, v0
	v_mov_b32_e32 v74, v0
	v_mov_b32_e32 v75, v0
	v_mov_b32_e32 v76, v0
	v_mov_b32_e32 v77, v0
	v_mov_b32_e32 v78, v0
	v_mov_b32_e32 v79, v0
	v_mov_b32_e32 v80, v0
	v_mov_b32_e32 v81, v0
	v_mov_b32_e32 v82, v0
	v_mov_b32_e32 v83, v0
	v_mov_b32_e32 v84, v0
	v_mov_b32_e32 v85, v0
	v_mov_b32_e32 v86, v0
	v_mov_b32_e32 v87, v0
	v_mov_b32_e32 v88, v0
	v_mov_b32_e32 v89, v0
	v_mov_b32_e32 v90, v0
	v_mov_b32_e32 v91, v0
	v_mov_b32_e32 v92, v0
	v_mov_b32_e32 v93, v0
	v_mov_b32_e32 v94, v0
	v_mov_b32_e32 v95, v0
	v_mov_b32_e32 v96, v0
	v_mov_b32_e32 v97, v0
	v_mov_b32_e32 v98, v0
	v_mov_b32_e32 v99, v0
	v_mov_b32_e32 v100, v0
	v_mov_b32_e32 v101, v0
	v_mov_b32_e32 v102, v0
	v_mov_b32_e32 v103, v0
	v_mov_b32_e32 v104, v0
	v_mov_b32_e32 v105, v0
	v_mov_b32_e32 v106, v0
	v_mov_b32_e32 v107, v0
	v_mov_b32_e32 v108, v0
	v_mov_b32_e32 v109, v0
	v_mov_b32_e32 v110, v0
	v_mov_b32_e32 v111, v0
	v_mov_b32_e32 v112, v0
	v_mov_b32_e32 v113, v0
	v_mov_b32_e32 v114, v0
	v_mov_b32_e32 v115, v0
	v_mov_b32_e32 v116, v0
	v_mov_b32_e32 v117, v0
	v_mov_b32_e32 v118, v0
	v_mov_b32_e32 v119, v0
	v_mov_b32_e32 v120, v0
	v_mov_b32_e32 v121, v0
	v_mov_b32_e32 v122, v0
	v_mov_b32_e32 v123, v0
	v_mov_b32_e32 v124, v0
	v_mov_b32_e32 v125, v0
	v_mov_b32_e32 v126, v0
	v_mov_b32_e32 v127, v0
	v_readfirstlane_b32 s40, v180
	v_readfirstlane_b32 s41, v181
	v_readfirstlane_b32 s42, v178
	v_readfirstlane_b32 s43, v179
	v_lshrrev_b32_e32 v198, 3, v182
	v_and_b32_e32 v199, 7, v182
	v_lshlrev_b32_e32 v198, 11, v198
	v_lshl_or_b32 v190, v199, 4, v198
	s_lshl_b32 s44, s33, 8
	s_sub_u32 s40, s40, s44
	s_subb_u32 s41, s41, 0
	s_sub_u32 s42, s42, s44
	s_subb_u32 s43, s43, 0
	s_add_u32 s40, s40, 0x2957980
	s_addc_u32 s41, s41, 0
	s_add_u32 s42, s42, 0x80
	s_addc_u32 s43, s43, 0
	v_add_u32_e32 v191, 0x10000, v190
	v_add_u32_e32 v192, 0x20000, v190
	v_add_u32_e32 v193, 0x30000, v190
	v_add_u32_e32 v194, 0x40000, v190
	v_add_u32_e32 v195, 0x50000, v190
	v_add_u32_e32 v196, 0x60000, v190
	v_add_u32_e32 v197, 0x70000, v190
	s_waitcnt lgkmcnt(0)
	s_barrier
	s_waitcnt vmcnt(0)
	ds_write_b128 v189, v[164:167]
	ds_write_b128 v189, v[128:131] offset:4608
	ds_write_b128 v189, v[132:135] offset:9216
	ds_write_b128 v189, v[136:139] offset:13824
	ds_write_b128 v189, v[144:147] offset:18432
	ds_write_b128 v189, v[148:151] offset:23040
	ds_write_b128 v189, v[152:155] offset:27648
	ds_write_b128 v189, v[156:159] offset:32256
	ds_write_b128 v189, v[140:143] offset:36864
	ds_write_b128 v189, v[160:163] offset:41472
	ds_write_b128 v189, v[168:171] offset:46080
	ds_write_b128 v189, v[172:175] offset:50688
	global_load_dwordx4 v[164:167], v190, s[40:41]
	global_load_dwordx4 v[128:131], v191, s[40:41]
	global_load_dwordx4 v[132:135], v192, s[40:41]
	global_load_dwordx4 v[136:139], v193, s[40:41]
	global_load_dwordx4 v[144:147], v194, s[40:41]
	global_load_dwordx4 v[148:151], v195, s[40:41]
	global_load_dwordx4 v[140:143], v190, s[42:43]
	global_load_dwordx4 v[160:163], v191, s[42:43]
	global_load_dwordx4 v[168:171], v192, s[42:43]
	global_load_dwordx4 v[172:175], v193, s[42:43]
	global_load_dwordx4 v[152:155], v196, s[40:41]
	global_load_dwordx4 v[156:159], v197, s[40:41]
	s_add_u32 s40, s40, 0x80
	s_addc_u32 s41, s41, 0
	s_add_u32 s42, s42, 0x80
	s_addc_u32 s43, s43, 0
	s_waitcnt lgkmcnt(0)
	s_barrier
.LBB0_302:
	ds_read_b128 v[216:219], v176 offset:36864
	ds_read_b128 v[200:203], v188
	ds_read_b128 v[220:223], v176 offset:41472
	ds_read_b128 v[204:207], v188 offset:4608
	ds_read_b128 v[208:211], v188 offset:9216
	ds_read_b128 v[212:215], v187
	s_waitcnt lgkmcnt(4)
	v_mfma_f32_32x32x16_bf16 v[112:127], v[200:203], v[216:219], v[112:127]
	ds_read_b128 v[240:243], v176 offset:36896
	s_waitcnt lgkmcnt(4)
	v_mfma_f32_32x32x16_bf16 v[96:111], v[200:203], v[220:223], v[96:111]
	ds_read_b128 v[224:227], v188 offset:32
	s_waitcnt lgkmcnt(4)
	v_mfma_f32_32x32x16_bf16 v[80:95], v[204:207], v[216:219], v[80:95]
	ds_read_b128 v[244:247], v176 offset:41504
	s_waitcnt lgkmcnt(5)
	v_mfma_f32_32x32x16_bf16 v[64:79], v[204:207], v[220:223], v[64:79]
	ds_read_b128 v[228:231], v188 offset:4640
	s_waitcnt lgkmcnt(5)
	v_mfma_f32_32x32x16_bf16 v[48:63], v[208:211], v[216:219], v[48:63]
	ds_read_b128 v[232:235], v188 offset:9248
	s_waitcnt lgkmcnt(6)
	v_mfma_f32_32x32x16_bf16 v[32:47], v[208:211], v[220:223], v[32:47]
	ds_read_b128 v[236:239], v187 offset:32
	s_waitcnt lgkmcnt(6)
	v_mfma_f32_32x32x16_bf16 v[16:31], v[212:215], v[216:219], v[16:31]
	s_waitcnt lgkmcnt(6)
	v_mfma_f32_32x32x16_bf16 v[0:15], v[212:215], v[220:223], v[0:15]
	s_waitcnt lgkmcnt(4)
	v_mfma_f32_32x32x16_bf16 v[112:127], v[224:227], v[240:243], v[112:127]
	ds_read_b128 v[200:203], v188 offset:64
	s_waitcnt lgkmcnt(4)
	v_mfma_f32_32x32x16_bf16 v[96:111], v[224:227], v[244:247], v[96:111]
	ds_read_b128 v[204:207], v188 offset:4672
	s_waitcnt lgkmcnt(4)
	v_mfma_f32_32x32x16_bf16 v[80:95], v[228:231], v[240:243], v[80:95]
	ds_read_b128 v[208:211], v188 offset:9280
	s_waitcnt lgkmcnt(5)
	v_mfma_f32_32x32x16_bf16 v[64:79], v[228:231], v[244:247], v[64:79]
	ds_read_b128 v[212:215], v187 offset:64
	s_waitcnt lgkmcnt(5)
	v_mfma_f32_32x32x16_bf16 v[48:63], v[232:235], v[240:243], v[48:63]
	ds_read_b128 v[216:219], v176 offset:36928
	s_waitcnt lgkmcnt(6)
	v_mfma_f32_32x32x16_bf16 v[32:47], v[232:235], v[244:247], v[32:47]
	ds_read_b128 v[220:223], v176 offset:41536
	s_waitcnt lgkmcnt(6)
	v_mfma_f32_32x32x16_bf16 v[16:31], v[236:239], v[240:243], v[16:31]
	s_waitcnt lgkmcnt(6)
	v_mfma_f32_32x32x16_bf16 v[0:15], v[236:239], v[244:247], v[0:15]
	s_waitcnt lgkmcnt(1)
	v_mfma_f32_32x32x16_bf16 v[112:127], v[200:203], v[216:219], v[112:127]
	ds_read_b128 v[224:227], v188 offset:96
	s_waitcnt lgkmcnt(1)
	v_mfma_f32_32x32x16_bf16 v[96:111], v[200:203], v[220:223], v[96:111]
	ds_read_b128 v[228:231], v188 offset:4704
	s_waitcnt lgkmcnt(3)
	v_mfma_f32_32x32x16_bf16 v[80:95], v[204:207], v[216:219], v[80:95]
	ds_read_b128 v[232:235], v188 offset:9312
	s_waitcnt lgkmcnt(3)
	v_mfma_f32_32x32x16_bf16 v[64:79], v[204:207], v[220:223], v[64:79]
	ds_read_b128 v[236:239], v187 offset:96
	s_waitcnt lgkmcnt(5)
	v_mfma_f32_32x32x16_bf16 v[48:63], v[208:211], v[216:219], v[48:63]
	ds_read_b128 v[240:243], v176 offset:36960
	s_waitcnt lgkmcnt(5)
	v_mfma_f32_32x32x16_bf16 v[32:47], v[208:211], v[220:223], v[32:47]
	ds_read_b128 v[244:247], v176 offset:41568
	s_waitcnt lgkmcnt(7)
	v_mfma_f32_32x32x16_bf16 v[16:31], v[212:215], v[216:219], v[16:31]
	s_waitcnt lgkmcnt(6)
	v_mfma_f32_32x32x16_bf16 v[0:15], v[212:215], v[220:223], v[0:15]
	s_waitcnt lgkmcnt(0)
	s_barrier
	s_waitcnt vmcnt(6)
	s_waitcnt lgkmcnt(1)
	v_mfma_f32_32x32x16_bf16 v[112:127], v[224:227], v[240:243], v[112:127]
	ds_write_b128 v189, v[164:167]
	ds_write_b128 v189, v[128:131] offset:4608
	s_waitcnt lgkmcnt(2)
	v_mfma_f32_32x32x16_bf16 v[96:111], v[224:227], v[244:247], v[96:111]
	ds_write_b128 v189, v[132:135] offset:9216
	global_load_dwordx4 v[164:167], v190, s[40:41]
	s_waitcnt lgkmcnt(4)
	v_mfma_f32_32x32x16_bf16 v[80:95], v[228:231], v[240:243], v[80:95]
	ds_write_b128 v189, v[136:139] offset:13824
	ds_write_b128 v189, v[144:147] offset:18432
	global_load_dwordx4 v[128:131], v191, s[40:41]
	s_waitcnt lgkmcnt(5)
	v_mfma_f32_32x32x16_bf16 v[64:79], v[228:231], v[244:247], v[64:79]
	ds_write_b128 v189, v[148:151] offset:23040
	global_load_dwordx4 v[132:135], v192, s[40:41]
	s_waitcnt lgkmcnt(7)
	v_mfma_f32_32x32x16_bf16 v[48:63], v[232:235], v[240:243], v[48:63]
	s_waitcnt vmcnt(8)
	ds_write_b128 v189, v[140:143] offset:36864
	s_waitcnt vmcnt(7)
	ds_write_b128 v189, v[160:163] offset:41472
	global_load_dwordx4 v[136:139], v193, s[40:41]
	s_waitcnt lgkmcnt(8)
	v_mfma_f32_32x32x16_bf16 v[32:47], v[232:235], v[244:247], v[32:47]
	s_waitcnt vmcnt(7)
	ds_write_b128 v189, v[168:171] offset:46080
	global_load_dwordx4 v[144:147], v194, s[40:41]
	s_waitcnt lgkmcnt(10)
	v_mfma_f32_32x32x16_bf16 v[16:31], v[236:239], v[240:243], v[16:31]
	s_waitcnt vmcnt(7)
	ds_write_b128 v189, v[172:175] offset:50688
	s_waitcnt vmcnt(6)
	ds_write_b128 v189, v[152:155] offset:27648
	global_load_dwordx4 v[148:151], v195, s[40:41]
	global_load_dwordx4 v[140:143], v190, s[42:43]
	global_load_dwordx4 v[160:163], v191, s[42:43]
	s_waitcnt lgkmcnt(11)
	v_mfma_f32_32x32x16_bf16 v[0:15], v[236:239], v[244:247], v[0:15]
	s_waitcnt vmcnt(8)
	ds_write_b128 v189, v[156:159] offset:32256
	global_load_dwordx4 v[168:171], v192, s[42:43]
	global_load_dwordx4 v[172:175], v193, s[42:43]
	global_load_dwordx4 v[152:155], v196, s[40:41]
	global_load_dwordx4 v[156:159], v197, s[40:41]
	s_add_u32 s40, s40, 0x80
	s_addc_u32 s41, s41, 0
	s_add_u32 s42, s42, 0x80
	s_addc_u32 s43, s43, 0
	s_add_u32 s16, s16, 0x80
	s_waitcnt lgkmcnt(0)
	s_barrier
	s_cmpk_lg_i32 s16, 0x780
	s_cbranch_scc1 .LBB0_302
	ds_read_b128 v[216:219], v176 offset:36864
	ds_read_b128 v[200:203], v188
	ds_read_b128 v[220:223], v176 offset:41472
	ds_read_b128 v[204:207], v188 offset:4608
	ds_read_b128 v[208:211], v188 offset:9216
	ds_read_b128 v[212:215], v187
	s_waitcnt lgkmcnt(4)
	v_mfma_f32_32x32x16_bf16 v[112:127], v[200:203], v[216:219], v[112:127]
	ds_read_b128 v[240:243], v176 offset:36896
	s_waitcnt lgkmcnt(4)
	v_mfma_f32_32x32x16_bf16 v[96:111], v[200:203], v[220:223], v[96:111]
	ds_read_b128 v[224:227], v188 offset:32
	s_waitcnt lgkmcnt(4)
	v_mfma_f32_32x32x16_bf16 v[80:95], v[204:207], v[216:219], v[80:95]
	ds_read_b128 v[244:247], v176 offset:41504
	s_waitcnt lgkmcnt(5)
	v_mfma_f32_32x32x16_bf16 v[64:79], v[204:207], v[220:223], v[64:79]
	ds_read_b128 v[228:231], v188 offset:4640
	s_waitcnt lgkmcnt(5)
	v_mfma_f32_32x32x16_bf16 v[48:63], v[208:211], v[216:219], v[48:63]
	ds_read_b128 v[232:235], v188 offset:9248
	s_waitcnt lgkmcnt(6)
	v_mfma_f32_32x32x16_bf16 v[32:47], v[208:211], v[220:223], v[32:47]
	ds_read_b128 v[236:239], v187 offset:32
	s_waitcnt lgkmcnt(6)
	v_mfma_f32_32x32x16_bf16 v[16:31], v[212:215], v[216:219], v[16:31]
	s_waitcnt lgkmcnt(6)
	v_mfma_f32_32x32x16_bf16 v[0:15], v[212:215], v[220:223], v[0:15]
	s_waitcnt lgkmcnt(4)
	v_mfma_f32_32x32x16_bf16 v[112:127], v[224:227], v[240:243], v[112:127]
	ds_read_b128 v[200:203], v188 offset:64
	s_waitcnt lgkmcnt(4)
	v_mfma_f32_32x32x16_bf16 v[96:111], v[224:227], v[244:247], v[96:111]
	ds_read_b128 v[204:207], v188 offset:4672
	s_waitcnt lgkmcnt(4)
	v_mfma_f32_32x32x16_bf16 v[80:95], v[228:231], v[240:243], v[80:95]
	ds_read_b128 v[208:211], v188 offset:9280
	s_waitcnt lgkmcnt(5)
	v_mfma_f32_32x32x16_bf16 v[64:79], v[228:231], v[244:247], v[64:79]
	ds_read_b128 v[212:215], v187 offset:64
	s_waitcnt lgkmcnt(5)
	v_mfma_f32_32x32x16_bf16 v[48:63], v[232:235], v[240:243], v[48:63]
	ds_read_b128 v[216:219], v176 offset:36928
	s_waitcnt lgkmcnt(6)
	v_mfma_f32_32x32x16_bf16 v[32:47], v[232:235], v[244:247], v[32:47]
	ds_read_b128 v[220:223], v176 offset:41536
	s_waitcnt lgkmcnt(6)
	v_mfma_f32_32x32x16_bf16 v[16:31], v[236:239], v[240:243], v[16:31]
	s_waitcnt lgkmcnt(6)
	v_mfma_f32_32x32x16_bf16 v[0:15], v[236:239], v[244:247], v[0:15]
	s_waitcnt lgkmcnt(1)
	v_mfma_f32_32x32x16_bf16 v[112:127], v[200:203], v[216:219], v[112:127]
	ds_read_b128 v[224:227], v188 offset:96
	s_waitcnt lgkmcnt(1)
	v_mfma_f32_32x32x16_bf16 v[96:111], v[200:203], v[220:223], v[96:111]
	ds_read_b128 v[228:231], v188 offset:4704
	s_waitcnt lgkmcnt(3)
	v_mfma_f32_32x32x16_bf16 v[80:95], v[204:207], v[216:219], v[80:95]
	ds_read_b128 v[232:235], v188 offset:9312
	s_waitcnt lgkmcnt(3)
	v_mfma_f32_32x32x16_bf16 v[64:79], v[204:207], v[220:223], v[64:79]
	ds_read_b128 v[236:239], v187 offset:96
	s_waitcnt lgkmcnt(5)
	v_mfma_f32_32x32x16_bf16 v[48:63], v[208:211], v[216:219], v[48:63]
	ds_read_b128 v[240:243], v176 offset:36960
	s_waitcnt lgkmcnt(5)
	v_mfma_f32_32x32x16_bf16 v[32:47], v[208:211], v[220:223], v[32:47]
	ds_read_b128 v[244:247], v176 offset:41568
	s_waitcnt lgkmcnt(7)
	v_mfma_f32_32x32x16_bf16 v[16:31], v[212:215], v[216:219], v[16:31]
	s_waitcnt lgkmcnt(6)
	v_mfma_f32_32x32x16_bf16 v[0:15], v[212:215], v[220:223], v[0:15]
	s_waitcnt lgkmcnt(1)
	v_mfma_f32_32x32x16_bf16 v[112:127], v[224:227], v[240:243], v[112:127]
	s_waitcnt lgkmcnt(0)
	v_mfma_f32_32x32x16_bf16 v[96:111], v[224:227], v[244:247], v[96:111]
	s_waitcnt lgkmcnt(1)
	v_mfma_f32_32x32x16_bf16 v[80:95], v[228:231], v[240:243], v[80:95]
	s_waitcnt lgkmcnt(0)
	v_mfma_f32_32x32x16_bf16 v[64:79], v[228:231], v[244:247], v[64:79]
	s_waitcnt lgkmcnt(1)
	v_mfma_f32_32x32x16_bf16 v[48:63], v[232:235], v[240:243], v[48:63]
	s_waitcnt lgkmcnt(0)
	v_mfma_f32_32x32x16_bf16 v[32:47], v[232:235], v[244:247], v[32:47]
	s_waitcnt lgkmcnt(1)
	v_mfma_f32_32x32x16_bf16 v[16:31], v[236:239], v[240:243], v[16:31]
	s_waitcnt lgkmcnt(0)
	v_mfma_f32_32x32x16_bf16 v[0:15], v[236:239], v[244:247], v[0:15]
	s_waitcnt vmcnt(0)
	s_mul_i32 s44, s12, 0x1240
	s_add_u32 s40, s30, s44
	s_addc_u32 s41, s31, 0
	s_lshl_b32 s44, s8, 1
	s_add_u32 s40, s40, s44
	s_addc_u32 s41, s41, 0
	s_add_u32 s40, s40, 0x7157900
	s_addc_u32 s41, s41, 0
	v_and_b32_e32 v131, 15, v182
	v_lshrrev_b32_e32 v172, 4, v182
	v_lshl_add_u32 v130, v131, 3, s8
	s_movk_i32 s44, 0x920
	v_cmp_gt_u32_e64 s[42:43], s44, v130
	v_mul_u32_u24_e32 v164, 0x1240, v172
	v_lshl_add_u32 v164, v131, 4, v164
	v_add_u32_e32 v165, 0x12400, v164
	v_add_u32_e32 v166, 0x24800, v164
	v_add_u32_e32 v167, 0x36c00, v164
	v_add_u32_e32 v168, 0x92000, v164
	v_add_u32_e32 v169, 0xa4400, v164
	v_add_u32_e32 v170, 0xb6800, v164
	v_add_u32_e32 v171, 0xc8c00, v164
	v_mul_u32_u24_e32 v129, 0x110, v172
	v_lshl_add_u32 v129, v131, 4, v129
	v_lshrrev_b32_e32 v131, 7, v182
	v_bfe_u32 v172, v182, 5, 1
	v_lshlrev_b32_e32 v131, 6, v131
	v_lshl_or_b32 v131, v172, 2, v131
	v_mul_u32_u24_e32 v131, 136, v131
	v_and_b32_e32 v172, 0x5f, v182
	v_add_lshl_u32 v128, v131, v172, 1
	s_barrier
	v_cvt_pk_bf16_f32 v112, v112, v113
	v_cvt_pk_bf16_f32 v114, v114, v115
	v_cvt_pk_bf16_f32 v116, v116, v117
	v_cvt_pk_bf16_f32 v118, v118, v119
	v_cvt_pk_bf16_f32 v120, v120, v121
	v_cvt_pk_bf16_f32 v122, v122, v123
	v_cvt_pk_bf16_f32 v124, v124, v125
	v_cvt_pk_bf16_f32 v126, v126, v127
	v_cvt_pk_bf16_f32 v96, v96, v97
	v_cvt_pk_bf16_f32 v98, v98, v99
	v_cvt_pk_bf16_f32 v100, v100, v101
	v_cvt_pk_bf16_f32 v102, v102, v103
	v_cvt_pk_bf16_f32 v104, v104, v105
	v_cvt_pk_bf16_f32 v106, v106, v107
	v_cvt_pk_bf16_f32 v108, v108, v109
	v_cvt_pk_bf16_f32 v110, v110, v111
	v_cvt_pk_bf16_f32 v80, v80, v81
	v_cvt_pk_bf16_f32 v82, v82, v83
	v_cvt_pk_bf16_f32 v84, v84, v85
	v_cvt_pk_bf16_f32 v86, v86, v87
	v_cvt_pk_bf16_f32 v88, v88, v89
	v_cvt_pk_bf16_f32 v90, v90, v91
	v_cvt_pk_bf16_f32 v92, v92, v93
	v_cvt_pk_bf16_f32 v94, v94, v95
	v_cvt_pk_bf16_f32 v64, v64, v65
	v_cvt_pk_bf16_f32 v66, v66, v67
	v_cvt_pk_bf16_f32 v68, v68, v69
	v_cvt_pk_bf16_f32 v70, v70, v71
	v_cvt_pk_bf16_f32 v72, v72, v73
	v_cvt_pk_bf16_f32 v74, v74, v75
	v_cvt_pk_bf16_f32 v76, v76, v77
	v_cvt_pk_bf16_f32 v78, v78, v79
	ds_write_b16 v128, v112
	ds_write_b16_d16_hi v128, v112 offset:272
	ds_write_b16 v128, v114 offset:544
	ds_write_b16_d16_hi v128, v114 offset:816
	ds_write_b16 v128, v116 offset:2176
	ds_write_b16_d16_hi v128, v116 offset:2448
	ds_write_b16 v128, v118 offset:2720
	ds_write_b16_d16_hi v128, v118 offset:2992
	ds_write_b16 v128, v120 offset:4352
	ds_write_b16_d16_hi v128, v120 offset:4624
	ds_write_b16 v128, v122 offset:4896
	ds_write_b16_d16_hi v128, v122 offset:5168
	ds_write_b16 v128, v124 offset:6528
	ds_write_b16_d16_hi v128, v124 offset:6800
	ds_write_b16 v128, v126 offset:7072
	ds_write_b16_d16_hi v128, v126 offset:7344
	ds_write_b16 v128, v96 offset:64
	ds_write_b16_d16_hi v128, v96 offset:336
	ds_write_b16 v128, v98 offset:608
	ds_write_b16_d16_hi v128, v98 offset:880
	ds_write_b16 v128, v100 offset:2240
	ds_write_b16_d16_hi v128, v100 offset:2512
	ds_write_b16 v128, v102 offset:2784
	ds_write_b16_d16_hi v128, v102 offset:3056
	ds_write_b16 v128, v104 offset:4416
	ds_write_b16_d16_hi v128, v104 offset:4688
	ds_write_b16 v128, v106 offset:4960
	ds_write_b16_d16_hi v128, v106 offset:5232
	ds_write_b16 v128, v108 offset:6592
	ds_write_b16_d16_hi v128, v108 offset:6864
	ds_write_b16 v128, v110 offset:7136
	ds_write_b16_d16_hi v128, v110 offset:7408
	ds_write_b16 v128, v80 offset:8704
	ds_write_b16_d16_hi v128, v80 offset:8976
	ds_write_b16 v128, v82 offset:9248
	ds_write_b16_d16_hi v128, v82 offset:9520
	ds_write_b16 v128, v84 offset:10880
	ds_write_b16_d16_hi v128, v84 offset:11152
	ds_write_b16 v128, v86 offset:11424
	ds_write_b16_d16_hi v128, v86 offset:11696
	ds_write_b16 v128, v88 offset:13056
	ds_write_b16_d16_hi v128, v88 offset:13328
	ds_write_b16 v128, v90 offset:13600
	ds_write_b16_d16_hi v128, v90 offset:13872
	ds_write_b16 v128, v92 offset:15232
	ds_write_b16_d16_hi v128, v92 offset:15504
	ds_write_b16 v128, v94 offset:15776
	ds_write_b16_d16_hi v128, v94 offset:16048
	ds_write_b16 v128, v64 offset:8768
	ds_write_b16_d16_hi v128, v64 offset:9040
	ds_write_b16 v128, v66 offset:9312
	ds_write_b16_d16_hi v128, v66 offset:9584
	ds_write_b16 v128, v68 offset:10944
	ds_write_b16_d16_hi v128, v68 offset:11216
	ds_write_b16 v128, v70 offset:11488
	ds_write_b16_d16_hi v128, v70 offset:11760
	ds_write_b16 v128, v72 offset:13120
	ds_write_b16_d16_hi v128, v72 offset:13392
	ds_write_b16 v128, v74 offset:13664
	ds_write_b16_d16_hi v128, v74 offset:13936
	ds_write_b16 v128, v76 offset:15296
	ds_write_b16_d16_hi v128, v76 offset:15568
	ds_write_b16 v128, v78 offset:15840
	ds_write_b16_d16_hi v128, v78 offset:16112
	s_waitcnt lgkmcnt(0)
	s_barrier
	ds_read_b128 v[132:135], v129
	ds_read_b128 v[136:139], v129 offset:4352
	ds_read_b128 v[140:143], v129 offset:8704
	ds_read_b128 v[144:147], v129 offset:13056
	ds_read_b128 v[148:151], v129 offset:17408
	ds_read_b128 v[152:155], v129 offset:21760
	ds_read_b128 v[156:159], v129 offset:26112
	ds_read_b128 v[160:163], v129 offset:30464
	v_cvt_pk_bf16_f32 v48, v48, v49
	v_cvt_pk_bf16_f32 v50, v50, v51
	v_cvt_pk_bf16_f32 v52, v52, v53
	v_cvt_pk_bf16_f32 v54, v54, v55
	v_cvt_pk_bf16_f32 v56, v56, v57
	v_cvt_pk_bf16_f32 v58, v58, v59
	v_cvt_pk_bf16_f32 v60, v60, v61
	v_cvt_pk_bf16_f32 v62, v62, v63
	v_cvt_pk_bf16_f32 v32, v32, v33
	v_cvt_pk_bf16_f32 v34, v34, v35
	v_cvt_pk_bf16_f32 v36, v36, v37
	v_cvt_pk_bf16_f32 v38, v38, v39
	v_cvt_pk_bf16_f32 v40, v40, v41
	v_cvt_pk_bf16_f32 v42, v42, v43
	v_cvt_pk_bf16_f32 v44, v44, v45
	v_cvt_pk_bf16_f32 v46, v46, v47
	v_cvt_pk_bf16_f32 v16, v16, v17
	v_cvt_pk_bf16_f32 v18, v18, v19
	v_cvt_pk_bf16_f32 v20, v20, v21
	v_cvt_pk_bf16_f32 v22, v22, v23
	v_cvt_pk_bf16_f32 v24, v24, v25
	v_cvt_pk_bf16_f32 v26, v26, v27
	v_cvt_pk_bf16_f32 v28, v28, v29
	v_cvt_pk_bf16_f32 v30, v30, v31
	v_cvt_pk_bf16_f32 v0, v0, v1
	v_cvt_pk_bf16_f32 v2, v2, v3
	v_cvt_pk_bf16_f32 v4, v4, v5
	v_cvt_pk_bf16_f32 v6, v6, v7
	v_cvt_pk_bf16_f32 v8, v8, v9
	v_cvt_pk_bf16_f32 v10, v10, v11
	v_cvt_pk_bf16_f32 v12, v12, v13
	v_cvt_pk_bf16_f32 v14, v14, v15
	s_and_saveexec_b64 s[46:47], s[42:43]
	s_waitcnt lgkmcnt(7)
	global_store_dwordx4 v164, v[132:135], s[40:41]
	s_waitcnt lgkmcnt(6)
	global_store_dwordx4 v165, v[136:139], s[40:41]
	s_waitcnt lgkmcnt(5)
	global_store_dwordx4 v166, v[140:143], s[40:41]
	s_waitcnt lgkmcnt(4)
	global_store_dwordx4 v167, v[144:147], s[40:41]
	s_waitcnt lgkmcnt(3)
	global_store_dwordx4 v168, v[148:151], s[40:41]
	s_waitcnt lgkmcnt(2)
	global_store_dwordx4 v169, v[152:155], s[40:41]
	s_waitcnt lgkmcnt(1)
	global_store_dwordx4 v170, v[156:159], s[40:41]
	s_waitcnt lgkmcnt(0)
	global_store_dwordx4 v171, v[160:163], s[40:41]
	s_or_b64 exec, exec, s[46:47]
	s_barrier
	ds_write_b16 v128, v48
	ds_write_b16_d16_hi v128, v48 offset:272
	ds_write_b16 v128, v50 offset:544
	ds_write_b16_d16_hi v128, v50 offset:816
	ds_write_b16 v128, v52 offset:2176
	ds_write_b16_d16_hi v128, v52 offset:2448
	ds_write_b16 v128, v54 offset:2720
	ds_write_b16_d16_hi v128, v54 offset:2992
	ds_write_b16 v128, v56 offset:4352
	ds_write_b16_d16_hi v128, v56 offset:4624
	ds_write_b16 v128, v58 offset:4896
	ds_write_b16_d16_hi v128, v58 offset:5168
	ds_write_b16 v128, v60 offset:6528
	ds_write_b16_d16_hi v128, v60 offset:6800
	ds_write_b16 v128, v62 offset:7072
	ds_write_b16_d16_hi v128, v62 offset:7344
	ds_write_b16 v128, v32 offset:64
	ds_write_b16_d16_hi v128, v32 offset:336
	ds_write_b16 v128, v34 offset:608
	ds_write_b16_d16_hi v128, v34 offset:880
	ds_write_b16 v128, v36 offset:2240
	ds_write_b16_d16_hi v128, v36 offset:2512
	ds_write_b16 v128, v38 offset:2784
	ds_write_b16_d16_hi v128, v38 offset:3056
	ds_write_b16 v128, v40 offset:4416
	ds_write_b16_d16_hi v128, v40 offset:4688
	ds_write_b16 v128, v42 offset:4960
	ds_write_b16_d16_hi v128, v42 offset:5232
	ds_write_b16 v128, v44 offset:6592
	ds_write_b16_d16_hi v128, v44 offset:6864
	ds_write_b16 v128, v46 offset:7136
	ds_write_b16_d16_hi v128, v46 offset:7408
	ds_write_b16 v128, v16 offset:8704
	ds_write_b16_d16_hi v128, v16 offset:8976
	ds_write_b16 v128, v18 offset:9248
	ds_write_b16_d16_hi v128, v18 offset:9520
	ds_write_b16 v128, v20 offset:10880
	ds_write_b16_d16_hi v128, v20 offset:11152
	ds_write_b16 v128, v22 offset:11424
	ds_write_b16_d16_hi v128, v22 offset:11696
	ds_write_b16 v128, v24 offset:13056
	ds_write_b16_d16_hi v128, v24 offset:13328
	ds_write_b16 v128, v26 offset:13600
	ds_write_b16_d16_hi v128, v26 offset:13872
	ds_write_b16 v128, v28 offset:15232
	ds_write_b16_d16_hi v128, v28 offset:15504
	ds_write_b16 v128, v30 offset:15776
	ds_write_b16_d16_hi v128, v30 offset:16048
	ds_write_b16 v128, v0 offset:8768
	ds_write_b16_d16_hi v128, v0 offset:9040
	ds_write_b16 v128, v2 offset:9312
	ds_write_b16_d16_hi v128, v2 offset:9584
	ds_write_b16 v128, v4 offset:10944
	ds_write_b16_d16_hi v128, v4 offset:11216
	ds_write_b16 v128, v6 offset:11488
	ds_write_b16_d16_hi v128, v6 offset:11760
	ds_write_b16 v128, v8 offset:13120
	ds_write_b16_d16_hi v128, v8 offset:13392
	ds_write_b16 v128, v10 offset:13664
	ds_write_b16_d16_hi v128, v10 offset:13936
	ds_write_b16 v128, v12 offset:15296
	ds_write_b16_d16_hi v128, v12 offset:15568
	ds_write_b16 v128, v14 offset:15840
	ds_write_b16_d16_hi v128, v14 offset:16112
	s_waitcnt lgkmcnt(0)
	s_barrier
	ds_read_b128 v[132:135], v129
	ds_read_b128 v[136:139], v129 offset:4352
	ds_read_b128 v[140:143], v129 offset:8704
	ds_read_b128 v[144:147], v129 offset:13056
	ds_read_b128 v[148:151], v129 offset:17408
	ds_read_b128 v[152:155], v129 offset:21760
	ds_read_b128 v[156:159], v129 offset:26112
	ds_read_b128 v[160:163], v129 offset:30464
	v_add_u32_e32 v164, 0x49000, v164
	v_add_u32_e32 v165, 0x49000, v165
	v_add_u32_e32 v166, 0x49000, v166
	v_add_u32_e32 v167, 0x49000, v167
	v_add_u32_e32 v168, 0x49000, v168
	v_add_u32_e32 v169, 0x49000, v169
	v_add_u32_e32 v170, 0x49000, v170
	v_add_u32_e32 v171, 0x49000, v171
	s_and_saveexec_b64 s[46:47], s[42:43]
	s_waitcnt lgkmcnt(7)
	global_store_dwordx4 v164, v[132:135], s[40:41]
	s_waitcnt lgkmcnt(6)
	global_store_dwordx4 v165, v[136:139], s[40:41]
	s_waitcnt lgkmcnt(5)
	global_store_dwordx4 v166, v[140:143], s[40:41]
	s_waitcnt lgkmcnt(4)
	global_store_dwordx4 v167, v[144:147], s[40:41]
	s_waitcnt lgkmcnt(3)
	global_store_dwordx4 v168, v[148:151], s[40:41]
	s_waitcnt lgkmcnt(2)
	global_store_dwordx4 v169, v[152:155], s[40:41]
	s_waitcnt lgkmcnt(1)
	global_store_dwordx4 v170, v[156:159], s[40:41]
	s_waitcnt lgkmcnt(0)
	global_store_dwordx4 v171, v[160:163], s[40:41]
	s_or_b64 exec, exec, s[46:47]
	s_branch .Lmt4_tail_0

.Lv5_c_1:
	ds_write_b128 v189, v[160:163]
	ds_write_b128 v189, v[128:131] offset:4608
	ds_write_b128 v189, v[132:135] offset:9216
	ds_write_b128 v189, v[136:139] offset:13824
	ds_write_b128 v189, v[140:143] offset:18432
	ds_write_b128 v189, v[144:147] offset:23040
	ds_write_b128 v189, v[148:151] offset:27648
	ds_write_b128 v189, v[156:159] offset:32256
	ds_write_b128 v189, v[152:155] offset:36864
	ds_write_b128 v189, v[164:167] offset:41472
	ds_write_b128 v189, v[168:171] offset:46080
	ds_write_b128 v189, v[172:175] offset:50688
	global_load_dwordx4 v[160:163], v190, s[38:39]
	global_load_dwordx4 v[128:131], v191, s[38:39]
	global_load_dwordx4 v[132:135], v192, s[38:39]
	global_load_dwordx4 v[136:139], v193, s[38:39]
	global_load_dwordx4 v[140:143], v194, s[38:39]
	global_load_dwordx4 v[144:147], v195, s[38:39]
	global_load_dwordx4 v[152:155], v190, s[40:41]
	global_load_dwordx4 v[164:167], v191, s[40:41]
	global_load_dwordx4 v[168:171], v192, s[40:41]
	global_load_dwordx4 v[172:175], v193, s[40:41]
	global_load_dwordx4 v[148:151], v196, s[38:39]
	global_load_dwordx4 v[156:159], v197, s[38:39]
	s_add_u32 s38, s38, 0x80
	s_addc_u32 s39, s39, 0
	s_add_u32 s40, s40, 0x80
	s_addc_u32 s41, s41, 0
	s_waitcnt lgkmcnt(0)
	s_barrier
.LBB0_997:
	ds_read_b128 v[216:219], v188 offset:36864
	ds_read_b128 v[200:203], v187
	ds_read_b128 v[220:223], v188 offset:41472
	ds_read_b128 v[204:207], v187 offset:4608
	ds_read_b128 v[208:211], v187 offset:9216
	ds_read_b128 v[212:215], v176
	s_waitcnt lgkmcnt(4)
	v_mfma_f32_32x32x16_bf16 v[112:127], v[200:203], v[216:219], v[112:127]
	ds_read_b128 v[240:243], v188 offset:36896
	s_waitcnt lgkmcnt(4)
	v_mfma_f32_32x32x16_bf16 v[96:111], v[200:203], v[220:223], v[96:111]
	ds_read_b128 v[224:227], v187 offset:32
	s_waitcnt lgkmcnt(4)
	v_mfma_f32_32x32x16_bf16 v[80:95], v[204:207], v[216:219], v[80:95]
	ds_read_b128 v[244:247], v188 offset:41504
	s_waitcnt lgkmcnt(5)
	v_mfma_f32_32x32x16_bf16 v[64:79], v[204:207], v[220:223], v[64:79]
	ds_read_b128 v[228:231], v187 offset:4640
	s_waitcnt lgkmcnt(5)
	v_mfma_f32_32x32x16_bf16 v[48:63], v[208:211], v[216:219], v[48:63]
	ds_read_b128 v[232:235], v187 offset:9248
	s_waitcnt lgkmcnt(6)
	v_mfma_f32_32x32x16_bf16 v[32:47], v[208:211], v[220:223], v[32:47]
	ds_read_b128 v[236:239], v176 offset:32
	s_waitcnt lgkmcnt(6)
	v_mfma_f32_32x32x16_bf16 v[16:31], v[212:215], v[216:219], v[16:31]
	s_waitcnt lgkmcnt(6)
	v_mfma_f32_32x32x16_bf16 v[0:15], v[212:215], v[220:223], v[0:15]
	s_waitcnt lgkmcnt(4)
	v_mfma_f32_32x32x16_bf16 v[112:127], v[224:227], v[240:243], v[112:127]
	ds_read_b128 v[200:203], v187 offset:64
	s_waitcnt lgkmcnt(4)
	v_mfma_f32_32x32x16_bf16 v[96:111], v[224:227], v[244:247], v[96:111]
	ds_read_b128 v[204:207], v187 offset:4672
	s_waitcnt lgkmcnt(4)
	v_mfma_f32_32x32x16_bf16 v[80:95], v[228:231], v[240:243], v[80:95]
	ds_read_b128 v[208:211], v187 offset:9280
	s_waitcnt lgkmcnt(5)
	v_mfma_f32_32x32x16_bf16 v[64:79], v[228:231], v[244:247], v[64:79]
	ds_read_b128 v[212:215], v176 offset:64
	s_waitcnt lgkmcnt(5)
	v_mfma_f32_32x32x16_bf16 v[48:63], v[232:235], v[240:243], v[48:63]
	ds_read_b128 v[216:219], v188 offset:36928
	s_waitcnt lgkmcnt(6)
	v_mfma_f32_32x32x16_bf16 v[32:47], v[232:235], v[244:247], v[32:47]
	ds_read_b128 v[220:223], v188 offset:41536
	s_waitcnt lgkmcnt(6)
	v_mfma_f32_32x32x16_bf16 v[16:31], v[236:239], v[240:243], v[16:31]
	s_waitcnt lgkmcnt(6)
	v_mfma_f32_32x32x16_bf16 v[0:15], v[236:239], v[244:247], v[0:15]
	s_waitcnt lgkmcnt(1)
	v_mfma_f32_32x32x16_bf16 v[112:127], v[200:203], v[216:219], v[112:127]
	ds_read_b128 v[224:227], v187 offset:96
	s_waitcnt lgkmcnt(1)
	v_mfma_f32_32x32x16_bf16 v[96:111], v[200:203], v[220:223], v[96:111]
	ds_read_b128 v[228:231], v187 offset:4704
	s_waitcnt lgkmcnt(3)
	v_mfma_f32_32x32x16_bf16 v[80:95], v[204:207], v[216:219], v[80:95]
	ds_read_b128 v[232:235], v187 offset:9312
	s_waitcnt lgkmcnt(3)
	v_mfma_f32_32x32x16_bf16 v[64:79], v[204:207], v[220:223], v[64:79]
	ds_read_b128 v[236:239], v176 offset:96
	s_waitcnt lgkmcnt(5)
	v_mfma_f32_32x32x16_bf16 v[48:63], v[208:211], v[216:219], v[48:63]
	ds_read_b128 v[240:243], v188 offset:36960
	s_waitcnt lgkmcnt(5)
	v_mfma_f32_32x32x16_bf16 v[32:47], v[208:211], v[220:223], v[32:47]
	ds_read_b128 v[244:247], v188 offset:41568
	s_waitcnt lgkmcnt(7)
	v_mfma_f32_32x32x16_bf16 v[16:31], v[212:215], v[216:219], v[16:31]
	s_waitcnt lgkmcnt(6)
	v_mfma_f32_32x32x16_bf16 v[0:15], v[212:215], v[220:223], v[0:15]
	s_waitcnt lgkmcnt(0)
	s_barrier
	s_waitcnt vmcnt(6)
	s_waitcnt lgkmcnt(1)
	v_mfma_f32_32x32x16_bf16 v[112:127], v[224:227], v[240:243], v[112:127]
	ds_write_b128 v189, v[160:163]
	ds_write_b128 v189, v[128:131] offset:4608
	s_waitcnt lgkmcnt(2)
	v_mfma_f32_32x32x16_bf16 v[96:111], v[224:227], v[244:247], v[96:111]
	ds_write_b128 v189, v[132:135] offset:9216
	global_load_dwordx4 v[160:163], v190, s[38:39]
	s_waitcnt lgkmcnt(4)
	v_mfma_f32_32x32x16_bf16 v[80:95], v[228:231], v[240:243], v[80:95]
	ds_write_b128 v189, v[136:139] offset:13824
	ds_write_b128 v189, v[140:143] offset:18432
	global_load_dwordx4 v[128:131], v191, s[38:39]
	s_waitcnt lgkmcnt(5)
	v_mfma_f32_32x32x16_bf16 v[64:79], v[228:231], v[244:247], v[64:79]
	ds_write_b128 v189, v[144:147] offset:23040
	global_load_dwordx4 v[132:135], v192, s[38:39]
	s_waitcnt lgkmcnt(7)
	v_mfma_f32_32x32x16_bf16 v[48:63], v[232:235], v[240:243], v[48:63]
	s_waitcnt vmcnt(8)
	ds_write_b128 v189, v[152:155] offset:36864
	s_waitcnt vmcnt(7)
	ds_write_b128 v189, v[164:167] offset:41472
	global_load_dwordx4 v[136:139], v193, s[38:39]
	s_waitcnt lgkmcnt(8)
	v_mfma_f32_32x32x16_bf16 v[32:47], v[232:235], v[244:247], v[32:47]
	s_waitcnt vmcnt(7)
	ds_write_b128 v189, v[168:171] offset:46080
	global_load_dwordx4 v[140:143], v194, s[38:39]
	s_waitcnt lgkmcnt(10)
	v_mfma_f32_32x32x16_bf16 v[16:31], v[236:239], v[240:243], v[16:31]
	s_waitcnt vmcnt(7)
	ds_write_b128 v189, v[172:175] offset:50688
	s_waitcnt vmcnt(6)
	ds_write_b128 v189, v[148:151] offset:27648
	global_load_dwordx4 v[144:147], v195, s[38:39]
	global_load_dwordx4 v[152:155], v190, s[40:41]
	global_load_dwordx4 v[164:167], v191, s[40:41]
	s_waitcnt lgkmcnt(11)
	v_mfma_f32_32x32x16_bf16 v[0:15], v[236:239], v[244:247], v[0:15]
	s_waitcnt vmcnt(8)
	ds_write_b128 v189, v[156:159] offset:32256
	global_load_dwordx4 v[168:171], v192, s[40:41]
	global_load_dwordx4 v[172:175], v193, s[40:41]
	global_load_dwordx4 v[148:151], v196, s[38:39]
	global_load_dwordx4 v[156:159], v197, s[38:39]
	s_add_u32 s38, s38, 0x80
	s_addc_u32 s39, s39, 0
	s_add_u32 s40, s40, 0x80
	s_addc_u32 s41, s41, 0
	s_add_u32 s12, s12, 0x80
	s_waitcnt lgkmcnt(0)
	s_barrier
	s_cmpk_lg_i32 s12, 0x780
	s_cbranch_scc1 .LBB0_997
	ds_read_b128 v[216:219], v188 offset:36864
	ds_read_b128 v[200:203], v187
	ds_read_b128 v[220:223], v188 offset:41472
	ds_read_b128 v[204:207], v187 offset:4608
	ds_read_b128 v[208:211], v187 offset:9216
	ds_read_b128 v[212:215], v176
	s_waitcnt lgkmcnt(4)
	v_mfma_f32_32x32x16_bf16 v[112:127], v[200:203], v[216:219], v[112:127]
	ds_read_b128 v[240:243], v188 offset:36896
	s_waitcnt lgkmcnt(4)
	v_mfma_f32_32x32x16_bf16 v[96:111], v[200:203], v[220:223], v[96:111]
	ds_read_b128 v[224:227], v187 offset:32
	s_waitcnt lgkmcnt(4)
	v_mfma_f32_32x32x16_bf16 v[80:95], v[204:207], v[216:219], v[80:95]
	ds_read_b128 v[244:247], v188 offset:41504
	s_waitcnt lgkmcnt(5)
	v_mfma_f32_32x32x16_bf16 v[64:79], v[204:207], v[220:223], v[64:79]
	ds_read_b128 v[228:231], v187 offset:4640
	s_waitcnt lgkmcnt(5)
	v_mfma_f32_32x32x16_bf16 v[48:63], v[208:211], v[216:219], v[48:63]
	ds_read_b128 v[232:235], v187 offset:9248
	s_waitcnt lgkmcnt(6)
	v_mfma_f32_32x32x16_bf16 v[32:47], v[208:211], v[220:223], v[32:47]
	ds_read_b128 v[236:239], v176 offset:32
	s_waitcnt lgkmcnt(6)
	v_mfma_f32_32x32x16_bf16 v[16:31], v[212:215], v[216:219], v[16:31]
	s_waitcnt lgkmcnt(6)
	v_mfma_f32_32x32x16_bf16 v[0:15], v[212:215], v[220:223], v[0:15]
	s_waitcnt lgkmcnt(4)
	v_mfma_f32_32x32x16_bf16 v[112:127], v[224:227], v[240:243], v[112:127]
	ds_read_b128 v[200:203], v187 offset:64
	s_waitcnt lgkmcnt(4)
	v_mfma_f32_32x32x16_bf16 v[96:111], v[224:227], v[244:247], v[96:111]
	ds_read_b128 v[204:207], v187 offset:4672
	s_waitcnt lgkmcnt(4)
	v_mfma_f32_32x32x16_bf16 v[80:95], v[228:231], v[240:243], v[80:95]
	ds_read_b128 v[208:211], v187 offset:9280
	s_waitcnt lgkmcnt(5)
	v_mfma_f32_32x32x16_bf16 v[64:79], v[228:231], v[244:247], v[64:79]
	ds_read_b128 v[212:215], v176 offset:64
	s_waitcnt lgkmcnt(5)
	v_mfma_f32_32x32x16_bf16 v[48:63], v[232:235], v[240:243], v[48:63]
	ds_read_b128 v[216:219], v188 offset:36928
	s_waitcnt lgkmcnt(6)
	v_mfma_f32_32x32x16_bf16 v[32:47], v[232:235], v[244:247], v[32:47]
	ds_read_b128 v[220:223], v188 offset:41536
	s_waitcnt lgkmcnt(6)
	v_mfma_f32_32x32x16_bf16 v[16:31], v[236:239], v[240:243], v[16:31]
	s_waitcnt lgkmcnt(6)
	v_mfma_f32_32x32x16_bf16 v[0:15], v[236:239], v[244:247], v[0:15]
	s_waitcnt lgkmcnt(1)
	v_mfma_f32_32x32x16_bf16 v[112:127], v[200:203], v[216:219], v[112:127]
	ds_read_b128 v[224:227], v187 offset:96
	s_waitcnt lgkmcnt(1)
	v_mfma_f32_32x32x16_bf16 v[96:111], v[200:203], v[220:223], v[96:111]
	ds_read_b128 v[228:231], v187 offset:4704
	s_waitcnt lgkmcnt(3)
	v_mfma_f32_32x32x16_bf16 v[80:95], v[204:207], v[216:219], v[80:95]
	ds_read_b128 v[232:235], v187 offset:9312
	s_waitcnt lgkmcnt(3)
	v_mfma_f32_32x32x16_bf16 v[64:79], v[204:207], v[220:223], v[64:79]
	ds_read_b128 v[236:239], v176 offset:96
	s_waitcnt lgkmcnt(5)
	v_mfma_f32_32x32x16_bf16 v[48:63], v[208:211], v[216:219], v[48:63]
	ds_read_b128 v[240:243], v188 offset:36960
	s_waitcnt lgkmcnt(5)
	v_mfma_f32_32x32x16_bf16 v[32:47], v[208:211], v[220:223], v[32:47]
	ds_read_b128 v[244:247], v188 offset:41568
	s_waitcnt lgkmcnt(7)
	v_mfma_f32_32x32x16_bf16 v[16:31], v[212:215], v[216:219], v[16:31]
	s_waitcnt lgkmcnt(6)
	v_mfma_f32_32x32x16_bf16 v[0:15], v[212:215], v[220:223], v[0:15]
	s_waitcnt lgkmcnt(1)
	v_mfma_f32_32x32x16_bf16 v[112:127], v[224:227], v[240:243], v[112:127]
	s_waitcnt lgkmcnt(0)
	v_mfma_f32_32x32x16_bf16 v[96:111], v[224:227], v[244:247], v[96:111]
	s_waitcnt lgkmcnt(1)
	v_mfma_f32_32x32x16_bf16 v[80:95], v[228:231], v[240:243], v[80:95]
	s_waitcnt lgkmcnt(0)
	v_mfma_f32_32x32x16_bf16 v[64:79], v[228:231], v[244:247], v[64:79]
	s_waitcnt lgkmcnt(1)
	v_mfma_f32_32x32x16_bf16 v[48:63], v[232:235], v[240:243], v[48:63]
	s_waitcnt lgkmcnt(0)
	v_mfma_f32_32x32x16_bf16 v[32:47], v[232:235], v[244:247], v[32:47]
	s_waitcnt lgkmcnt(1)
	v_mfma_f32_32x32x16_bf16 v[16:31], v[236:239], v[240:243], v[16:31]
	s_waitcnt lgkmcnt(0)
	v_mfma_f32_32x32x16_bf16 v[0:15], v[236:239], v[244:247], v[0:15]
	s_waitcnt vmcnt(0)
	s_mul_i32 s42, s6, 0x2000
	s_add_u32 s44, s30, s42
	s_addc_u32 s45, s31, 0
	s_lshl_b32 s42, s58, 1
	s_add_u32 s44, s44, s42
	s_addc_u32 s45, s45, 0
	s_add_u32 s44, s44, 0x7157900
	s_addc_u32 s45, s45, 0
	s_mov_b32 s43, 1
	v_max_f32_e32 v112, 0, v112
	v_max_f32_e32 v113, 0, v113
	v_mul_f32_e32 v112, v112, v112
	v_mul_f32_e32 v113, v113, v113
	v_cvt_pk_bf16_f32 v190, v112, v113
	v_max_f32_e32 v114, 0, v114
	v_max_f32_e32 v115, 0, v115
	v_mul_f32_e32 v114, v114, v114
	v_mul_f32_e32 v115, v115, v115
	v_cvt_pk_bf16_f32 v191, v114, v115
	v_max_f32_e32 v116, 0, v116
	v_max_f32_e32 v117, 0, v117
	v_mul_f32_e32 v116, v116, v116
	v_mul_f32_e32 v117, v117, v117
	v_cvt_pk_bf16_f32 v192, v116, v117
	v_max_f32_e32 v118, 0, v118
	v_max_f32_e32 v119, 0, v119
	v_mul_f32_e32 v118, v118, v118
	v_mul_f32_e32 v119, v119, v119
	v_cvt_pk_bf16_f32 v193, v118, v119
	v_max_f32_e32 v120, 0, v120
	v_max_f32_e32 v121, 0, v121
	v_mul_f32_e32 v120, v120, v120
	v_mul_f32_e32 v121, v121, v121
	v_cvt_pk_bf16_f32 v194, v120, v121
	v_max_f32_e32 v122, 0, v122
	v_max_f32_e32 v123, 0, v123
	v_mul_f32_e32 v122, v122, v122
	v_mul_f32_e32 v123, v123, v123
	v_cvt_pk_bf16_f32 v195, v122, v123
	v_max_f32_e32 v124, 0, v124
	v_max_f32_e32 v125, 0, v125
	v_mul_f32_e32 v124, v124, v124
	v_mul_f32_e32 v125, v125, v125
	v_cvt_pk_bf16_f32 v196, v124, v125
	v_max_f32_e32 v126, 0, v126
	v_max_f32_e32 v127, 0, v127
	v_mul_f32_e32 v126, v126, v126
	v_mul_f32_e32 v127, v127, v127
	v_cvt_pk_bf16_f32 v197, v126, v127
	v_max_f32_e32 v96, 0, v96
	v_max_f32_e32 v97, 0, v97
	v_mul_f32_e32 v96, v96, v96
	v_mul_f32_e32 v97, v97, v97
	v_cvt_pk_bf16_f32 v198, v96, v97
	v_max_f32_e32 v98, 0, v98
	v_max_f32_e32 v99, 0, v99
	v_mul_f32_e32 v98, v98, v98
	v_mul_f32_e32 v99, v99, v99
	v_cvt_pk_bf16_f32 v199, v98, v99
	v_max_f32_e32 v100, 0, v100
	v_max_f32_e32 v101, 0, v101
	v_mul_f32_e32 v100, v100, v100
	v_mul_f32_e32 v101, v101, v101
	v_cvt_pk_bf16_f32 v200, v100, v101
	v_max_f32_e32 v102, 0, v102
	v_max_f32_e32 v103, 0, v103
	v_mul_f32_e32 v102, v102, v102
	v_mul_f32_e32 v103, v103, v103
	v_cvt_pk_bf16_f32 v201, v102, v103
	v_max_f32_e32 v104, 0, v104
	v_max_f32_e32 v105, 0, v105
	v_mul_f32_e32 v104, v104, v104
	v_mul_f32_e32 v105, v105, v105
	v_cvt_pk_bf16_f32 v202, v104, v105
	v_max_f32_e32 v106, 0, v106
	v_max_f32_e32 v107, 0, v107
	v_mul_f32_e32 v106, v106, v106
	v_mul_f32_e32 v107, v107, v107
	v_cvt_pk_bf16_f32 v203, v106, v107
	v_max_f32_e32 v108, 0, v108
	v_max_f32_e32 v109, 0, v109
	v_mul_f32_e32 v108, v108, v108
	v_mul_f32_e32 v109, v109, v109
	v_cvt_pk_bf16_f32 v204, v108, v109
	v_max_f32_e32 v110, 0, v110
	v_max_f32_e32 v111, 0, v111
	v_mul_f32_e32 v110, v110, v110
	v_mul_f32_e32 v111, v111, v111
	v_cvt_pk_bf16_f32 v205, v110, v111
	v_max_f32_e32 v80, 0, v80
	v_max_f32_e32 v81, 0, v81
	v_mul_f32_e32 v80, v80, v80
	v_mul_f32_e32 v81, v81, v81
	v_cvt_pk_bf16_f32 v206, v80, v81
	v_max_f32_e32 v82, 0, v82
	v_max_f32_e32 v83, 0, v83
	v_mul_f32_e32 v82, v82, v82
	v_mul_f32_e32 v83, v83, v83
	v_cvt_pk_bf16_f32 v207, v82, v83
	v_max_f32_e32 v84, 0, v84
	v_max_f32_e32 v85, 0, v85
	v_mul_f32_e32 v84, v84, v84
	v_mul_f32_e32 v85, v85, v85
	v_cvt_pk_bf16_f32 v208, v84, v85
	v_max_f32_e32 v86, 0, v86
	v_max_f32_e32 v87, 0, v87
	v_mul_f32_e32 v86, v86, v86
	v_mul_f32_e32 v87, v87, v87
	v_cvt_pk_bf16_f32 v209, v86, v87
	v_max_f32_e32 v88, 0, v88
	v_max_f32_e32 v89, 0, v89
	v_mul_f32_e32 v88, v88, v88
	v_mul_f32_e32 v89, v89, v89
	v_cvt_pk_bf16_f32 v210, v88, v89
	v_max_f32_e32 v90, 0, v90
	v_max_f32_e32 v91, 0, v91
	v_mul_f32_e32 v90, v90, v90
	v_mul_f32_e32 v91, v91, v91
	v_cvt_pk_bf16_f32 v211, v90, v91
	v_max_f32_e32 v92, 0, v92
	v_max_f32_e32 v93, 0, v93
	v_mul_f32_e32 v92, v92, v92
	v_mul_f32_e32 v93, v93, v93
	v_cvt_pk_bf16_f32 v212, v92, v93
	v_max_f32_e32 v94, 0, v94
	v_max_f32_e32 v95, 0, v95
	v_mul_f32_e32 v94, v94, v94
	v_mul_f32_e32 v95, v95, v95
	v_cvt_pk_bf16_f32 v213, v94, v95
	v_max_f32_e32 v64, 0, v64
	v_max_f32_e32 v65, 0, v65
	v_mul_f32_e32 v64, v64, v64
	v_mul_f32_e32 v65, v65, v65
	v_cvt_pk_bf16_f32 v214, v64, v65
	v_max_f32_e32 v66, 0, v66
	v_max_f32_e32 v67, 0, v67
	v_mul_f32_e32 v66, v66, v66
	v_mul_f32_e32 v67, v67, v67
	v_cvt_pk_bf16_f32 v215, v66, v67
	v_max_f32_e32 v68, 0, v68
	v_max_f32_e32 v69, 0, v69
	v_mul_f32_e32 v68, v68, v68
	v_mul_f32_e32 v69, v69, v69
	v_cvt_pk_bf16_f32 v216, v68, v69
	v_max_f32_e32 v70, 0, v70
	v_max_f32_e32 v71, 0, v71
	v_mul_f32_e32 v70, v70, v70
	v_mul_f32_e32 v71, v71, v71
	v_cvt_pk_bf16_f32 v217, v70, v71
	v_max_f32_e32 v72, 0, v72
	v_max_f32_e32 v73, 0, v73
	v_mul_f32_e32 v72, v72, v72
	v_mul_f32_e32 v73, v73, v73
	v_cvt_pk_bf16_f32 v218, v72, v73
	v_max_f32_e32 v74, 0, v74
	v_max_f32_e32 v75, 0, v75
	v_mul_f32_e32 v74, v74, v74
	v_mul_f32_e32 v75, v75, v75
	v_cvt_pk_bf16_f32 v219, v74, v75
	v_max_f32_e32 v76, 0, v76
	v_max_f32_e32 v77, 0, v77
	v_mul_f32_e32 v76, v76, v76
	v_mul_f32_e32 v77, v77, v77
	v_cvt_pk_bf16_f32 v220, v76, v77
	v_max_f32_e32 v78, 0, v78
	v_max_f32_e32 v79, 0, v79
	v_mul_f32_e32 v78, v78, v78
	v_mul_f32_e32 v79, v79, v79
	v_cvt_pk_bf16_f32 v221, v78, v79
	v_max_f32_e32 v48, 0, v48
	v_max_f32_e32 v49, 0, v49
	v_mul_f32_e32 v48, v48, v48
	v_mul_f32_e32 v49, v49, v49
	v_cvt_pk_bf16_f32 v222, v48, v49
	v_max_f32_e32 v50, 0, v50
	v_max_f32_e32 v51, 0, v51
	v_mul_f32_e32 v50, v50, v50
	v_mul_f32_e32 v51, v51, v51
	v_cvt_pk_bf16_f32 v223, v50, v51
	v_max_f32_e32 v52, 0, v52
	v_max_f32_e32 v53, 0, v53
	v_mul_f32_e32 v52, v52, v52
	v_mul_f32_e32 v53, v53, v53
	v_cvt_pk_bf16_f32 v224, v52, v53
	v_max_f32_e32 v54, 0, v54
	v_max_f32_e32 v55, 0, v55
	v_mul_f32_e32 v54, v54, v54
	v_mul_f32_e32 v55, v55, v55
	v_cvt_pk_bf16_f32 v225, v54, v55
	v_max_f32_e32 v56, 0, v56
	v_max_f32_e32 v57, 0, v57
	v_mul_f32_e32 v56, v56, v56
	v_mul_f32_e32 v57, v57, v57
	v_cvt_pk_bf16_f32 v226, v56, v57
	v_max_f32_e32 v58, 0, v58
	v_max_f32_e32 v59, 0, v59
	v_mul_f32_e32 v58, v58, v58
	v_mul_f32_e32 v59, v59, v59
	v_cvt_pk_bf16_f32 v227, v58, v59
	v_max_f32_e32 v60, 0, v60
	v_max_f32_e32 v61, 0, v61
	v_mul_f32_e32 v60, v60, v60
	v_mul_f32_e32 v61, v61, v61
	v_cvt_pk_bf16_f32 v228, v60, v61
	v_max_f32_e32 v62, 0, v62
	v_max_f32_e32 v63, 0, v63
	v_mul_f32_e32 v62, v62, v62
	v_mul_f32_e32 v63, v63, v63
	v_cvt_pk_bf16_f32 v229, v62, v63
	v_max_f32_e32 v32, 0, v32
	v_max_f32_e32 v33, 0, v33
	v_mul_f32_e32 v32, v32, v32
	v_mul_f32_e32 v33, v33, v33
	v_cvt_pk_bf16_f32 v230, v32, v33
	v_max_f32_e32 v34, 0, v34
	v_max_f32_e32 v35, 0, v35
	v_mul_f32_e32 v34, v34, v34
	v_mul_f32_e32 v35, v35, v35
	v_cvt_pk_bf16_f32 v231, v34, v35
	v_max_f32_e32 v36, 0, v36
	v_max_f32_e32 v37, 0, v37
	v_mul_f32_e32 v36, v36, v36
	v_mul_f32_e32 v37, v37, v37
	v_cvt_pk_bf16_f32 v232, v36, v37
	v_max_f32_e32 v38, 0, v38
	v_max_f32_e32 v39, 0, v39
	v_mul_f32_e32 v38, v38, v38
	v_mul_f32_e32 v39, v39, v39
	v_cvt_pk_bf16_f32 v233, v38, v39
	v_max_f32_e32 v40, 0, v40
	v_max_f32_e32 v41, 0, v41
	v_mul_f32_e32 v40, v40, v40
	v_mul_f32_e32 v41, v41, v41
	v_cvt_pk_bf16_f32 v234, v40, v41
	v_max_f32_e32 v42, 0, v42
	v_max_f32_e32 v43, 0, v43
	v_mul_f32_e32 v42, v42, v42
	v_mul_f32_e32 v43, v43, v43
	v_cvt_pk_bf16_f32 v235, v42, v43
	v_max_f32_e32 v44, 0, v44
	v_max_f32_e32 v45, 0, v45
	v_mul_f32_e32 v44, v44, v44
	v_mul_f32_e32 v45, v45, v45
	v_cvt_pk_bf16_f32 v236, v44, v45
	v_max_f32_e32 v46, 0, v46
	v_max_f32_e32 v47, 0, v47
	v_mul_f32_e32 v46, v46, v46
	v_mul_f32_e32 v47, v47, v47
	v_cvt_pk_bf16_f32 v237, v46, v47
	v_max_f32_e32 v16, 0, v16
	v_max_f32_e32 v17, 0, v17
	v_mul_f32_e32 v16, v16, v16
	v_mul_f32_e32 v17, v17, v17
	v_cvt_pk_bf16_f32 v238, v16, v17
	v_max_f32_e32 v18, 0, v18
	v_max_f32_e32 v19, 0, v19
	v_mul_f32_e32 v18, v18, v18
	v_mul_f32_e32 v19, v19, v19
	v_cvt_pk_bf16_f32 v239, v18, v19
	v_max_f32_e32 v20, 0, v20
	v_max_f32_e32 v21, 0, v21
	v_mul_f32_e32 v20, v20, v20
	v_mul_f32_e32 v21, v21, v21
	v_cvt_pk_bf16_f32 v240, v20, v21
	v_max_f32_e32 v22, 0, v22
	v_max_f32_e32 v23, 0, v23
	v_mul_f32_e32 v22, v22, v22
	v_mul_f32_e32 v23, v23, v23
	v_cvt_pk_bf16_f32 v241, v22, v23
	v_max_f32_e32 v24, 0, v24
	v_max_f32_e32 v25, 0, v25
	v_mul_f32_e32 v24, v24, v24
	v_mul_f32_e32 v25, v25, v25
	v_cvt_pk_bf16_f32 v242, v24, v25
	v_max_f32_e32 v26, 0, v26
	v_max_f32_e32 v27, 0, v27
	v_mul_f32_e32 v26, v26, v26
	v_mul_f32_e32 v27, v27, v27
	v_cvt_pk_bf16_f32 v243, v26, v27
	v_max_f32_e32 v28, 0, v28
	v_max_f32_e32 v29, 0, v29
	v_mul_f32_e32 v28, v28, v28
	v_mul_f32_e32 v29, v29, v29
	v_cvt_pk_bf16_f32 v244, v28, v29
	v_max_f32_e32 v30, 0, v30
	v_max_f32_e32 v31, 0, v31
	v_mul_f32_e32 v30, v30, v30
	v_mul_f32_e32 v31, v31, v31
	v_cvt_pk_bf16_f32 v245, v30, v31
	v_max_f32_e32 v0, 0, v0
	v_max_f32_e32 v1, 0, v1
	v_mul_f32_e32 v0, v0, v0
	v_mul_f32_e32 v1, v1, v1
	v_cvt_pk_bf16_f32 v246, v0, v1
	v_max_f32_e32 v2, 0, v2
	v_max_f32_e32 v3, 0, v3
	v_mul_f32_e32 v2, v2, v2
	v_mul_f32_e32 v3, v3, v3
	v_cvt_pk_bf16_f32 v247, v2, v3
	v_max_f32_e32 v4, 0, v4
	v_max_f32_e32 v5, 0, v5
	v_mul_f32_e32 v4, v4, v4
	v_mul_f32_e32 v5, v5, v5
	v_cvt_pk_bf16_f32 v248, v4, v5
	v_max_f32_e32 v6, 0, v6
	v_max_f32_e32 v7, 0, v7
	v_mul_f32_e32 v6, v6, v6
	v_mul_f32_e32 v7, v7, v7
	v_cvt_pk_bf16_f32 v249, v6, v7
	v_max_f32_e32 v8, 0, v8
	v_max_f32_e32 v9, 0, v9
	v_mul_f32_e32 v8, v8, v8
	v_mul_f32_e32 v9, v9, v9
	v_cvt_pk_bf16_f32 v250, v8, v9
	v_max_f32_e32 v10, 0, v10
	v_max_f32_e32 v11, 0, v11
	v_mul_f32_e32 v10, v10, v10
	v_mul_f32_e32 v11, v11, v11
	v_cvt_pk_bf16_f32 v251, v10, v11
	v_max_f32_e32 v12, 0, v12
	v_max_f32_e32 v13, 0, v13
	v_mul_f32_e32 v12, v12, v12
	v_mul_f32_e32 v13, v13, v13
	v_cvt_pk_bf16_f32 v252, v12, v13
	v_max_f32_e32 v14, 0, v14
	v_max_f32_e32 v15, 0, v15
	v_mul_f32_e32 v14, v14, v14
	v_mul_f32_e32 v15, v15, v15
	v_cvt_pk_bf16_f32 v253, v14, v15
	s_add_i32 s57, s57, s22
	s_add_i32 s56, s56, s22
	s_cmpk_lt_u32 s57, 0x240
	s_cbranch_scc1 .LBB0_996
	v_and_b32_e32 v3, 15, v182
	v_lshrrev_b32_e32 v4, 4, v182
	v_mul_u32_u24_e32 v2, 0x2000, v4
	v_lshl_add_u32 v2, v3, 4, v2
	v_mul_u32_u24_e32 v1, 0x110, v4
	v_lshl_add_u32 v1, v3, 4, v1
	v_lshrrev_b32_e32 v3, 7, v182
	v_bfe_u32 v4, v182, 5, 1
	v_lshlrev_b32_e32 v3, 6, v3
	v_lshl_or_b32 v3, v4, 2, v3
	v_mul_u32_u24_e32 v3, 136, v3
	v_and_b32_e32 v4, 0x5f, v182
	v_add_lshl_u32 v0, v3, v4, 1
	s_barrier
	ds_write_b16 v0, v190
	ds_write_b16_d16_hi v0, v190 offset:272
	ds_write_b16 v0, v191 offset:544
	ds_write_b16_d16_hi v0, v191 offset:816
	ds_write_b16 v0, v192 offset:2176
	ds_write_b16_d16_hi v0, v192 offset:2448
	ds_write_b16 v0, v193 offset:2720
	ds_write_b16_d16_hi v0, v193 offset:2992
	ds_write_b16 v0, v194 offset:4352
	ds_write_b16_d16_hi v0, v194 offset:4624
	ds_write_b16 v0, v195 offset:4896
	ds_write_b16_d16_hi v0, v195 offset:5168
	ds_write_b16 v0, v196 offset:6528
	ds_write_b16_d16_hi v0, v196 offset:6800
	ds_write_b16 v0, v197 offset:7072
	ds_write_b16_d16_hi v0, v197 offset:7344
	ds_write_b16 v0, v198 offset:64
	ds_write_b16_d16_hi v0, v198 offset:336
	ds_write_b16 v0, v199 offset:608
	ds_write_b16_d16_hi v0, v199 offset:880
	ds_write_b16 v0, v200 offset:2240
	ds_write_b16_d16_hi v0, v200 offset:2512
	ds_write_b16 v0, v201 offset:2784
	ds_write_b16_d16_hi v0, v201 offset:3056
	ds_write_b16 v0, v202 offset:4416
	ds_write_b16_d16_hi v0, v202 offset:4688
	ds_write_b16 v0, v203 offset:4960
	ds_write_b16_d16_hi v0, v203 offset:5232
	ds_write_b16 v0, v204 offset:6592
	ds_write_b16_d16_hi v0, v204 offset:6864
	ds_write_b16 v0, v205 offset:7136
	ds_write_b16_d16_hi v0, v205 offset:7408
	ds_write_b16 v0, v206 offset:8704
	ds_write_b16_d16_hi v0, v206 offset:8976
	ds_write_b16 v0, v207 offset:9248
	ds_write_b16_d16_hi v0, v207 offset:9520
	ds_write_b16 v0, v208 offset:10880
	ds_write_b16_d16_hi v0, v208 offset:11152
	ds_write_b16 v0, v209 offset:11424
	ds_write_b16_d16_hi v0, v209 offset:11696
	ds_write_b16 v0, v210 offset:13056
	ds_write_b16_d16_hi v0, v210 offset:13328
	ds_write_b16 v0, v211 offset:13600
	ds_write_b16_d16_hi v0, v211 offset:13872
	ds_write_b16 v0, v212 offset:15232
	ds_write_b16_d16_hi v0, v212 offset:15504
	ds_write_b16 v0, v213 offset:15776
	ds_write_b16_d16_hi v0, v213 offset:16048
	ds_write_b16 v0, v214 offset:8768
	ds_write_b16_d16_hi v0, v214 offset:9040
	ds_write_b16 v0, v215 offset:9312
	ds_write_b16_d16_hi v0, v215 offset:9584
	ds_write_b16 v0, v216 offset:10944
	ds_write_b16_d16_hi v0, v216 offset:11216
	ds_write_b16 v0, v217 offset:11488
	ds_write_b16_d16_hi v0, v217 offset:11760
	ds_write_b16 v0, v218 offset:13120
	ds_write_b16_d16_hi v0, v218 offset:13392
	ds_write_b16 v0, v219 offset:13664
	ds_write_b16_d16_hi v0, v219 offset:13936
	ds_write_b16 v0, v220 offset:15296
	ds_write_b16_d16_hi v0, v220 offset:15568
	ds_write_b16 v0, v221 offset:15840
	ds_write_b16_d16_hi v0, v221 offset:16112
	s_waitcnt lgkmcnt(0)
	s_barrier
	ds_read_b128 v[8:11], v1
	ds_read_b128 v[12:15], v1 offset:4352
	ds_read_b128 v[16:19], v1 offset:8704
	ds_read_b128 v[20:23], v1 offset:13056
	ds_read_b128 v[24:27], v1 offset:17408
	ds_read_b128 v[28:31], v1 offset:21760
	ds_read_b128 v[32:35], v1 offset:26112
	ds_read_b128 v[36:39], v1 offset:30464
	s_add_u32 s38, s44, 0x0
	s_addc_u32 s39, s45, 0
	s_waitcnt lgkmcnt(7)
	global_store_dwordx4 v2, v[8:11], s[38:39]
	s_add_u32 s38, s44, 0x20000
	s_addc_u32 s39, s45, 0
	s_waitcnt lgkmcnt(6)
	global_store_dwordx4 v2, v[12:15], s[38:39]
	s_add_u32 s38, s44, 0x40000
	s_addc_u32 s39, s45, 0
	s_waitcnt lgkmcnt(5)
	global_store_dwordx4 v2, v[16:19], s[38:39]
	s_add_u32 s38, s44, 0x60000
	s_addc_u32 s39, s45, 0
	s_waitcnt lgkmcnt(4)
	global_store_dwordx4 v2, v[20:23], s[38:39]
	s_add_u32 s38, s44, 0x100000
	s_addc_u32 s39, s45, 0
	s_waitcnt lgkmcnt(3)
	global_store_dwordx4 v2, v[24:27], s[38:39]
	s_add_u32 s38, s44, 0x120000
	s_addc_u32 s39, s45, 0
	s_waitcnt lgkmcnt(2)
	global_store_dwordx4 v2, v[28:31], s[38:39]
	s_add_u32 s38, s44, 0x140000
	s_addc_u32 s39, s45, 0
	s_waitcnt lgkmcnt(1)
	global_store_dwordx4 v2, v[32:35], s[38:39]
	s_add_u32 s38, s44, 0x160000
	s_addc_u32 s39, s45, 0
	s_waitcnt lgkmcnt(0)
	global_store_dwordx4 v2, v[36:39], s[38:39]
	s_barrier
	ds_write_b16 v0, v222
	ds_write_b16_d16_hi v0, v222 offset:272
	ds_write_b16 v0, v223 offset:544
	ds_write_b16_d16_hi v0, v223 offset:816
	ds_write_b16 v0, v224 offset:2176
	ds_write_b16_d16_hi v0, v224 offset:2448
	ds_write_b16 v0, v225 offset:2720
	ds_write_b16_d16_hi v0, v225 offset:2992
	ds_write_b16 v0, v226 offset:4352
	ds_write_b16_d16_hi v0, v226 offset:4624
	ds_write_b16 v0, v227 offset:4896
	ds_write_b16_d16_hi v0, v227 offset:5168
	ds_write_b16 v0, v228 offset:6528
	ds_write_b16_d16_hi v0, v228 offset:6800
	ds_write_b16 v0, v229 offset:7072
	ds_write_b16_d16_hi v0, v229 offset:7344
	ds_write_b16 v0, v230 offset:64
	ds_write_b16_d16_hi v0, v230 offset:336
	ds_write_b16 v0, v231 offset:608
	ds_write_b16_d16_hi v0, v231 offset:880
	ds_write_b16 v0, v232 offset:2240
	ds_write_b16_d16_hi v0, v232 offset:2512
	ds_write_b16 v0, v233 offset:2784
	ds_write_b16_d16_hi v0, v233 offset:3056
	ds_write_b16 v0, v234 offset:4416
	ds_write_b16_d16_hi v0, v234 offset:4688
	ds_write_b16 v0, v235 offset:4960
	ds_write_b16_d16_hi v0, v235 offset:5232
	ds_write_b16 v0, v236 offset:6592
	ds_write_b16_d16_hi v0, v236 offset:6864
	ds_write_b16 v0, v237 offset:7136
	ds_write_b16_d16_hi v0, v237 offset:7408
	ds_write_b16 v0, v238 offset:8704
	ds_write_b16_d16_hi v0, v238 offset:8976
	ds_write_b16 v0, v239 offset:9248
	ds_write_b16_d16_hi v0, v239 offset:9520
	ds_write_b16 v0, v240 offset:10880
	ds_write_b16_d16_hi v0, v240 offset:11152
	ds_write_b16 v0, v241 offset:11424
	ds_write_b16_d16_hi v0, v241 offset:11696
	ds_write_b16 v0, v242 offset:13056
	ds_write_b16_d16_hi v0, v242 offset:13328
	ds_write_b16 v0, v243 offset:13600
	ds_write_b16_d16_hi v0, v243 offset:13872
	ds_write_b16 v0, v244 offset:15232
	ds_write_b16_d16_hi v0, v244 offset:15504
	ds_write_b16 v0, v245 offset:15776
	ds_write_b16_d16_hi v0, v245 offset:16048
	ds_write_b16 v0, v246 offset:8768
	ds_write_b16_d16_hi v0, v246 offset:9040
	ds_write_b16 v0, v247 offset:9312
	ds_write_b16_d16_hi v0, v247 offset:9584
	ds_write_b16 v0, v248 offset:10944
	ds_write_b16_d16_hi v0, v248 offset:11216
	ds_write_b16 v0, v249 offset:11488
	ds_write_b16_d16_hi v0, v249 offset:11760
	ds_write_b16 v0, v250 offset:13120
	ds_write_b16_d16_hi v0, v250 offset:13392
	ds_write_b16 v0, v251 offset:13664
	ds_write_b16_d16_hi v0, v251 offset:13936
	ds_write_b16 v0, v252 offset:15296
	ds_write_b16_d16_hi v0, v252 offset:15568
	ds_write_b16 v0, v253 offset:15840
	ds_write_b16_d16_hi v0, v253 offset:16112
	s_waitcnt lgkmcnt(0)
	s_barrier
	ds_read_b128 v[8:11], v1
	ds_read_b128 v[12:15], v1 offset:4352
	ds_read_b128 v[16:19], v1 offset:8704
	ds_read_b128 v[20:23], v1 offset:13056
	ds_read_b128 v[24:27], v1 offset:17408
	ds_read_b128 v[28:31], v1 offset:21760
	ds_read_b128 v[32:35], v1 offset:26112
	ds_read_b128 v[36:39], v1 offset:30464
	s_add_u32 s38, s44, 0x80000
	s_addc_u32 s39, s45, 0
	s_waitcnt lgkmcnt(7)
	global_store_dwordx4 v2, v[8:11], s[38:39]
	s_add_u32 s38, s44, 0xa0000
	s_addc_u32 s39, s45, 0
	s_waitcnt lgkmcnt(6)
	global_store_dwordx4 v2, v[12:15], s[38:39]
	s_add_u32 s38, s44, 0xc0000
	s_addc_u32 s39, s45, 0
	s_waitcnt lgkmcnt(5)
	global_store_dwordx4 v2, v[16:19], s[38:39]
	s_add_u32 s38, s44, 0xe0000
	s_addc_u32 s39, s45, 0
	s_waitcnt lgkmcnt(4)
	global_store_dwordx4 v2, v[20:23], s[38:39]
	s_add_u32 s38, s44, 0x180000
	s_addc_u32 s39, s45, 0
	s_waitcnt lgkmcnt(3)
	global_store_dwordx4 v2, v[24:27], s[38:39]
	s_add_u32 s38, s44, 0x1a0000
	s_addc_u32 s39, s45, 0
	s_waitcnt lgkmcnt(2)
	global_store_dwordx4 v2, v[28:31], s[38:39]
	s_add_u32 s38, s44, 0x1c0000
	s_addc_u32 s39, s45, 0
	s_waitcnt lgkmcnt(1)
	global_store_dwordx4 v2, v[32:35], s[38:39]
	s_add_u32 s38, s44, 0x1e0000
	s_addc_u32 s39, s45, 0
	s_waitcnt lgkmcnt(0)
	global_store_dwordx4 v2, v[36:39], s[38:39]
	s_mov_b32 s43, 0
	s_branch .LBB0_989

.LBB0_1282:
	s_mul_hi_u32 s0, s56, s25
	s_mul_i32 s1, s0, s20
	s_sub_i32 s1, s56, s1
	s_add_i32 s8, s0, 1
	s_sub_i32 s12, s1, s20
	s_cmp_ge_u32 s1, s20
	s_cselect_b32 s0, s8, s0
	s_cselect_b32 s1, s12, s1
	s_add_i32 s8, s0, 1
	s_cmp_ge_u32 s1, s20
	s_cselect_b32 s1, s8, s0
	s_add_i32 s0, s1, s23
	s_mul_i32 s1, s1, s20
	s_sub_i32 s1, s56, s1
	s_add_i32 s1, s1, s19
	s_mul_i32 s8, s0, 0xe38e3900
	v_alignbit_b32 v0, s8, s8, 8
	s_cmp_lt_u32 s1, 8
	v_cmp_gt_u32_e32 vcc, s26, v0
	s_cselect_b64 s[12:13], -1, 0
	s_and_b64 s[12:13], vcc, s[12:13]
	s_and_b64 vcc, exec, s[12:13]
	s_cbranch_vccnz .LBB0_1281
	s_lshl_b32 s12, s0, 8
	s_lshl_b32 s8, s1, 7
	s_mov_b64 s[0:1], s[30:31]
	v_mov_b32_e32 v0, v177
	s_mov_b32 s13, s9
	v_mbcnt_lo_u32_b32 v0, -1, v0
	v_mbcnt_hi_u32_b32 v0, -1, v0
	v_add_u32_e32 v182, s33, v0
	s_lshl_b64 s[16:17], s[12:13], 11
	v_ashrrev_i32_e32 v0, 3, v182
	v_lshlrev_b32_e32 v1, 3, v182
	s_add_u32 s58, s14, s16
	v_and_b32_e32 v6, 56, v1
	v_lshlrev_b32_e32 v1, 11, v0
	s_addc_u32 s59, s15, s17
	v_lshl_or_b32 v176, v6, 1, v1
	v_mul_lo_u32 v7, v0, s21
	v_lshl_add_u64 v[0:1], s[58:59], 0, v[176:177]
	v_add_co_u32_e32 v2, vcc, s27, v0
	s_lshl_b64 s[60:61], s[8:9], 11
	s_nop 0
	v_addc_co_u32_e32 v3, vcc, 0, v1, vcc
	v_add_co_u32_e32 v4, vcc, s34, v0
	s_add_u32 s60, s30, s60
	s_nop 0
	v_addc_co_u32_e32 v5, vcc, 0, v1, vcc
	global_load_dwordx4 v[128:131], v[2:3], off
	global_load_dwordx4 v[132:135], v[4:5], off
	v_add_co_u32_e32 v2, vcc, s35, v0
	s_addc_u32 s61, s31, s61
	s_nop 0
	v_addc_co_u32_e32 v3, vcc, 0, v1, vcc
	v_add_co_u32_e32 v4, vcc, s36, v0
	v_lshl_add_u64 v[178:179], s[60:61], 0, v[176:177]
	s_nop 0
	v_addc_co_u32_e32 v5, vcc, 0, v1, vcc
	global_load_dwordx4 v[136:139], v[2:3], off
	global_load_dwordx4 v[144:147], v[4:5], off
	v_add_co_u32_e32 v2, vcc, s37, v0
	v_bfe_u32 v185, v182, 6, 1
	s_nop 0
	v_addc_co_u32_e32 v3, vcc, 0, v1, vcc
	v_add_co_u32_e32 v4, vcc, s38, v0
	v_and_b32_e32 v184, 31, v182
	s_nop 0
	v_addc_co_u32_e32 v5, vcc, 0, v1, vcc
	v_add_co_u32_e32 v0, vcc, s39, v0
	global_load_dwordx4 v[148:151], v[2:3], off
	global_load_dwordx4 v[152:155], v[4:5], off
	v_addc_co_u32_e32 v1, vcc, 0, v1, vcc
	v_add_co_u32_e32 v2, vcc, s27, v178
	global_load_dwordx4 v[164:167], v176, s[58:59]
	global_load_dwordx4 v[140:143], v176, s[60:61]
	v_addc_co_u32_e32 v3, vcc, 0, v179, vcc
	global_load_dwordx4 v[156:159], v[0:1], off
	global_load_dwordx4 v[160:163], v[2:3], off
	v_add_co_u32_e32 v0, vcc, s34, v178
	v_bfe_u32 v186, v182, 5, 1
	s_nop 0
	v_addc_co_u32_e32 v1, vcc, 0, v179, vcc
	v_add_co_u32_e32 v2, vcc, s35, v178
	s_add_u32 s16, s30, s16
	s_nop 0
	v_addc_co_u32_e32 v3, vcc, 0, v179, vcc
	global_load_dwordx4 v[168:171], v[0:1], off
	global_load_dwordx4 v[172:175], v[2:3], off
	v_and_b32_e32 v0, 0xfffff9f, v182
	v_lshl_or_b32 v2, v185, 6, v184
	v_mul_lo_u32 v3, v0, s40
	v_or_b32_e32 v0, 0x60, v182
	v_lshlrev_b32_e32 v1, 4, v186
	v_mul_lo_u32 v4, v0, s40
	v_mul_u32_u24_e32 v2, 0x90, v2
	s_addc_u32 s17, s31, s17
	v_mov_b32_e32 v0, 0
	v_add_lshl_u32 v189, v7, v6, 1
	v_lshl_add_u64 v[180:181], s[16:17], 0, v[176:177]
	s_mov_b64 s[16:17], 0
	v_add_u32_e32 v188, v1, v3
	v_add_u32_e32 v187, v1, v4
	v_add_u32_e32 v176, v1, v2
	v_mov_b32_e32 v1, v0
	v_mov_b32_e32 v2, v0
	v_mov_b32_e32 v3, v0
	v_mov_b32_e32 v4, v0
	v_mov_b32_e32 v5, v0
	v_mov_b32_e32 v6, v0
	v_mov_b32_e32 v7, v0
	v_mov_b32_e32 v8, v0
	v_mov_b32_e32 v9, v0
	v_mov_b32_e32 v10, v0
	v_mov_b32_e32 v11, v0
	v_mov_b32_e32 v12, v0
	v_mov_b32_e32 v13, v0
	v_mov_b32_e32 v14, v0
	v_mov_b32_e32 v15, v0
	v_mov_b32_e32 v16, v0
	v_mov_b32_e32 v17, v0
	v_mov_b32_e32 v18, v0
	v_mov_b32_e32 v19, v0
	v_mov_b32_e32 v20, v0
	v_mov_b32_e32 v21, v0
	v_mov_b32_e32 v22, v0
	v_mov_b32_e32 v23, v0
	v_mov_b32_e32 v24, v0
	v_mov_b32_e32 v25, v0
	v_mov_b32_e32 v26, v0
	v_mov_b32_e32 v27, v0
	v_mov_b32_e32 v28, v0
	v_mov_b32_e32 v29, v0
	v_mov_b32_e32 v30, v0
	v_mov_b32_e32 v31, v0
	v_mov_b32_e32 v32, v0
	v_mov_b32_e32 v33, v0
	v_mov_b32_e32 v34, v0
	v_mov_b32_e32 v35, v0
	v_mov_b32_e32 v36, v0
	v_mov_b32_e32 v37, v0
	v_mov_b32_e32 v38, v0
	v_mov_b32_e32 v39, v0
	v_mov_b32_e32 v40, v0
	v_mov_b32_e32 v41, v0
	v_mov_b32_e32 v42, v0
	v_mov_b32_e32 v43, v0
	v_mov_b32_e32 v44, v0
	v_mov_b32_e32 v45, v0
	v_mov_b32_e32 v46, v0
	v_mov_b32_e32 v47, v0
	v_mov_b32_e32 v48, v0
	v_mov_b32_e32 v49, v0
	v_mov_b32_e32 v50, v0
	v_mov_b32_e32 v51, v0
	v_mov_b32_e32 v52, v0
	v_mov_b32_e32 v53, v0
	v_mov_b32_e32 v54, v0
	v_mov_b32_e32 v55, v0
	v_mov_b32_e32 v56, v0
	v_mov_b32_e32 v57, v0
	v_mov_b32_e32 v58, v0
	v_mov_b32_e32 v59, v0
	v_mov_b32_e32 v60, v0
	v_mov_b32_e32 v61, v0
	v_mov_b32_e32 v62, v0
	v_mov_b32_e32 v63, v0
	v_mov_b32_e32 v64, v0
	v_mov_b32_e32 v65, v0
	v_mov_b32_e32 v66, v0
	v_mov_b32_e32 v67, v0
	v_mov_b32_e32 v68, v0
	v_mov_b32_e32 v69, v0
	v_mov_b32_e32 v70, v0
	v_mov_b32_e32 v71, v0
	v_mov_b32_e32 v72, v0
	v_mov_b32_e32 v73, v0
	v_mov_b32_e32 v74, v0
	v_mov_b32_e32 v75, v0
	v_mov_b32_e32 v76, v0
	v_mov_b32_e32 v77, v0
	v_mov_b32_e32 v78, v0
	v_mov_b32_e32 v79, v0
	v_mov_b32_e32 v80, v0
	v_mov_b32_e32 v81, v0
	v_mov_b32_e32 v82, v0
	v_mov_b32_e32 v83, v0
	v_mov_b32_e32 v84, v0
	v_mov_b32_e32 v85, v0
	v_mov_b32_e32 v86, v0
	v_mov_b32_e32 v87, v0
	v_mov_b32_e32 v88, v0
	v_mov_b32_e32 v89, v0
	v_mov_b32_e32 v90, v0
	v_mov_b32_e32 v91, v0
	v_mov_b32_e32 v92, v0
	v_mov_b32_e32 v93, v0
	v_mov_b32_e32 v94, v0
	v_mov_b32_e32 v95, v0
	v_mov_b32_e32 v96, v0
	v_mov_b32_e32 v97, v0
	v_mov_b32_e32 v98, v0
	v_mov_b32_e32 v99, v0
	v_mov_b32_e32 v100, v0
	v_mov_b32_e32 v101, v0
	v_mov_b32_e32 v102, v0
	v_mov_b32_e32 v103, v0
	v_mov_b32_e32 v104, v0
	v_mov_b32_e32 v105, v0
	v_mov_b32_e32 v106, v0
	v_mov_b32_e32 v107, v0
	v_mov_b32_e32 v108, v0
	v_mov_b32_e32 v109, v0
	v_mov_b32_e32 v110, v0
	v_mov_b32_e32 v111, v0
	v_mov_b32_e32 v112, v0
	v_mov_b32_e32 v113, v0
	v_mov_b32_e32 v114, v0
	v_mov_b32_e32 v115, v0
	v_mov_b32_e32 v116, v0
	v_mov_b32_e32 v117, v0
	v_mov_b32_e32 v118, v0
	v_mov_b32_e32 v119, v0
	v_mov_b32_e32 v120, v0
	v_mov_b32_e32 v121, v0
	v_mov_b32_e32 v122, v0
	v_mov_b32_e32 v123, v0
	v_mov_b32_e32 v124, v0
	v_mov_b32_e32 v125, v0
	v_mov_b32_e32 v126, v0
	v_mov_b32_e32 v127, v0
	v_readfirstlane_b32 s42, v180
	v_readfirstlane_b32 s43, v181
	v_readfirstlane_b32 s44, v178
	v_readfirstlane_b32 s45, v179
	v_lshrrev_b32_e32 v198, 3, v182
	v_and_b32_e32 v199, 7, v182
	v_lshlrev_b32_e32 v198, 11, v198
	v_lshl_or_b32 v190, v199, 4, v198
	s_lshl_b32 s41, s33, 8
	s_sub_u32 s42, s42, s41
	s_subb_u32 s43, s43, 0
	s_sub_u32 s44, s44, s41
	s_subb_u32 s45, s45, 0
	s_add_u32 s42, s42, 0x2957980
	s_addc_u32 s43, s43, 0
	s_add_u32 s44, s44, 0x80
	s_addc_u32 s45, s45, 0
	v_add_u32_e32 v191, 0x10000, v190
	v_add_u32_e32 v192, 0x20000, v190
	v_add_u32_e32 v193, 0x30000, v190
	v_add_u32_e32 v194, 0x40000, v190
	v_add_u32_e32 v195, 0x50000, v190
	v_add_u32_e32 v196, 0x60000, v190
	v_add_u32_e32 v197, 0x70000, v190
	s_waitcnt lgkmcnt(0)
	s_barrier
	s_waitcnt vmcnt(0)
	ds_write_b128 v189, v[164:167]
	ds_write_b128 v189, v[128:131] offset:4608
	ds_write_b128 v189, v[132:135] offset:9216
	ds_write_b128 v189, v[136:139] offset:13824
	ds_write_b128 v189, v[144:147] offset:18432
	ds_write_b128 v189, v[148:151] offset:23040
	ds_write_b128 v189, v[152:155] offset:27648
	ds_write_b128 v189, v[156:159] offset:32256
	ds_write_b128 v189, v[140:143] offset:36864
	ds_write_b128 v189, v[160:163] offset:41472
	ds_write_b128 v189, v[168:171] offset:46080
	ds_write_b128 v189, v[172:175] offset:50688
	global_load_dwordx4 v[164:167], v190, s[42:43]
	global_load_dwordx4 v[128:131], v191, s[42:43]
	global_load_dwordx4 v[132:135], v192, s[42:43]
	global_load_dwordx4 v[136:139], v193, s[42:43]
	global_load_dwordx4 v[144:147], v194, s[42:43]
	global_load_dwordx4 v[148:151], v195, s[42:43]
	global_load_dwordx4 v[140:143], v190, s[44:45]
	global_load_dwordx4 v[160:163], v191, s[44:45]
	global_load_dwordx4 v[168:171], v192, s[44:45]
	global_load_dwordx4 v[172:175], v193, s[44:45]
	global_load_dwordx4 v[152:155], v196, s[42:43]
	global_load_dwordx4 v[156:159], v197, s[42:43]
	s_add_u32 s42, s42, 0x80
	s_addc_u32 s43, s43, 0
	s_add_u32 s44, s44, 0x80
	s_addc_u32 s45, s45, 0
	s_waitcnt lgkmcnt(0)
	s_barrier
.LBB0_1284:
	ds_read_b128 v[216:219], v176 offset:36864
	ds_read_b128 v[200:203], v188
	ds_read_b128 v[220:223], v176 offset:41472
	ds_read_b128 v[204:207], v188 offset:4608
	ds_read_b128 v[208:211], v188 offset:9216
	ds_read_b128 v[212:215], v187
	s_waitcnt lgkmcnt(4)
	v_mfma_f32_32x32x16_bf16 v[112:127], v[200:203], v[216:219], v[112:127]
	ds_read_b128 v[240:243], v176 offset:36896
	s_waitcnt lgkmcnt(4)
	v_mfma_f32_32x32x16_bf16 v[96:111], v[200:203], v[220:223], v[96:111]
	ds_read_b128 v[224:227], v188 offset:32
	s_waitcnt lgkmcnt(4)
	v_mfma_f32_32x32x16_bf16 v[80:95], v[204:207], v[216:219], v[80:95]
	ds_read_b128 v[244:247], v176 offset:41504
	s_waitcnt lgkmcnt(5)
	v_mfma_f32_32x32x16_bf16 v[64:79], v[204:207], v[220:223], v[64:79]
	ds_read_b128 v[228:231], v188 offset:4640
	s_waitcnt lgkmcnt(5)
	v_mfma_f32_32x32x16_bf16 v[48:63], v[208:211], v[216:219], v[48:63]
	ds_read_b128 v[232:235], v188 offset:9248
	s_waitcnt lgkmcnt(6)
	v_mfma_f32_32x32x16_bf16 v[32:47], v[208:211], v[220:223], v[32:47]
	ds_read_b128 v[236:239], v187 offset:32
	s_waitcnt lgkmcnt(6)
	v_mfma_f32_32x32x16_bf16 v[16:31], v[212:215], v[216:219], v[16:31]
	s_waitcnt lgkmcnt(6)
	v_mfma_f32_32x32x16_bf16 v[0:15], v[212:215], v[220:223], v[0:15]
	s_waitcnt lgkmcnt(4)
	v_mfma_f32_32x32x16_bf16 v[112:127], v[224:227], v[240:243], v[112:127]
	ds_read_b128 v[200:203], v188 offset:64
	s_waitcnt lgkmcnt(4)
	v_mfma_f32_32x32x16_bf16 v[96:111], v[224:227], v[244:247], v[96:111]
	ds_read_b128 v[204:207], v188 offset:4672
	s_waitcnt lgkmcnt(4)
	v_mfma_f32_32x32x16_bf16 v[80:95], v[228:231], v[240:243], v[80:95]
	ds_read_b128 v[208:211], v188 offset:9280
	s_waitcnt lgkmcnt(5)
	v_mfma_f32_32x32x16_bf16 v[64:79], v[228:231], v[244:247], v[64:79]
	ds_read_b128 v[212:215], v187 offset:64
	s_waitcnt lgkmcnt(5)
	v_mfma_f32_32x32x16_bf16 v[48:63], v[232:235], v[240:243], v[48:63]
	ds_read_b128 v[216:219], v176 offset:36928
	s_waitcnt lgkmcnt(6)
	v_mfma_f32_32x32x16_bf16 v[32:47], v[232:235], v[244:247], v[32:47]
	ds_read_b128 v[220:223], v176 offset:41536
	s_waitcnt lgkmcnt(6)
	v_mfma_f32_32x32x16_bf16 v[16:31], v[236:239], v[240:243], v[16:31]
	s_waitcnt lgkmcnt(6)
	v_mfma_f32_32x32x16_bf16 v[0:15], v[236:239], v[244:247], v[0:15]
	s_waitcnt lgkmcnt(1)
	v_mfma_f32_32x32x16_bf16 v[112:127], v[200:203], v[216:219], v[112:127]
	ds_read_b128 v[224:227], v188 offset:96
	s_waitcnt lgkmcnt(1)
	v_mfma_f32_32x32x16_bf16 v[96:111], v[200:203], v[220:223], v[96:111]
	ds_read_b128 v[228:231], v188 offset:4704
	s_waitcnt lgkmcnt(3)
	v_mfma_f32_32x32x16_bf16 v[80:95], v[204:207], v[216:219], v[80:95]
	ds_read_b128 v[232:235], v188 offset:9312
	s_waitcnt lgkmcnt(3)
	v_mfma_f32_32x32x16_bf16 v[64:79], v[204:207], v[220:223], v[64:79]
	ds_read_b128 v[236:239], v187 offset:96
	s_waitcnt lgkmcnt(5)
	v_mfma_f32_32x32x16_bf16 v[48:63], v[208:211], v[216:219], v[48:63]
	ds_read_b128 v[240:243], v176 offset:36960
	s_waitcnt lgkmcnt(5)
	v_mfma_f32_32x32x16_bf16 v[32:47], v[208:211], v[220:223], v[32:47]
	ds_read_b128 v[244:247], v176 offset:41568
	s_waitcnt lgkmcnt(7)
	v_mfma_f32_32x32x16_bf16 v[16:31], v[212:215], v[216:219], v[16:31]
	s_waitcnt lgkmcnt(6)
	v_mfma_f32_32x32x16_bf16 v[0:15], v[212:215], v[220:223], v[0:15]
	s_waitcnt lgkmcnt(0)
	s_barrier
	s_waitcnt vmcnt(6)
	s_waitcnt lgkmcnt(1)
	v_mfma_f32_32x32x16_bf16 v[112:127], v[224:227], v[240:243], v[112:127]
	ds_write_b128 v189, v[164:167]
	ds_write_b128 v189, v[128:131] offset:4608
	s_waitcnt lgkmcnt(2)
	v_mfma_f32_32x32x16_bf16 v[96:111], v[224:227], v[244:247], v[96:111]
	ds_write_b128 v189, v[132:135] offset:9216
	global_load_dwordx4 v[164:167], v190, s[42:43]
	s_waitcnt lgkmcnt(4)
	v_mfma_f32_32x32x16_bf16 v[80:95], v[228:231], v[240:243], v[80:95]
	ds_write_b128 v189, v[136:139] offset:13824
	ds_write_b128 v189, v[144:147] offset:18432
	global_load_dwordx4 v[128:131], v191, s[42:43]
	s_waitcnt lgkmcnt(5)
	v_mfma_f32_32x32x16_bf16 v[64:79], v[228:231], v[244:247], v[64:79]
	ds_write_b128 v189, v[148:151] offset:23040
	global_load_dwordx4 v[132:135], v192, s[42:43]
	s_waitcnt lgkmcnt(7)
	v_mfma_f32_32x32x16_bf16 v[48:63], v[232:235], v[240:243], v[48:63]
	s_waitcnt vmcnt(8)
	ds_write_b128 v189, v[140:143] offset:36864
	s_waitcnt vmcnt(7)
	ds_write_b128 v189, v[160:163] offset:41472
	global_load_dwordx4 v[136:139], v193, s[42:43]
	s_waitcnt lgkmcnt(8)
	v_mfma_f32_32x32x16_bf16 v[32:47], v[232:235], v[244:247], v[32:47]
	s_waitcnt vmcnt(7)
	ds_write_b128 v189, v[168:171] offset:46080
	global_load_dwordx4 v[144:147], v194, s[42:43]
	s_waitcnt lgkmcnt(10)
	v_mfma_f32_32x32x16_bf16 v[16:31], v[236:239], v[240:243], v[16:31]
	s_waitcnt vmcnt(7)
	ds_write_b128 v189, v[172:175] offset:50688
	s_waitcnt vmcnt(6)
	ds_write_b128 v189, v[152:155] offset:27648
	global_load_dwordx4 v[148:151], v195, s[42:43]
	global_load_dwordx4 v[140:143], v190, s[44:45]
	global_load_dwordx4 v[160:163], v191, s[44:45]
	s_waitcnt lgkmcnt(11)
	v_mfma_f32_32x32x16_bf16 v[0:15], v[236:239], v[244:247], v[0:15]
	s_waitcnt vmcnt(8)
	ds_write_b128 v189, v[156:159] offset:32256
	global_load_dwordx4 v[168:171], v192, s[44:45]
	global_load_dwordx4 v[172:175], v193, s[44:45]
	global_load_dwordx4 v[152:155], v196, s[42:43]
	global_load_dwordx4 v[156:159], v197, s[42:43]
	s_add_u32 s42, s42, 0x80
	s_addc_u32 s43, s43, 0
	s_add_u32 s44, s44, 0x80
	s_addc_u32 s45, s45, 0
	s_add_u32 s16, s16, 0x80
	s_waitcnt lgkmcnt(0)
	s_barrier
	s_cmpk_lg_i32 s16, 0x780
	s_cbranch_scc1 .LBB0_1284
	ds_read_b128 v[216:219], v176 offset:36864
	ds_read_b128 v[200:203], v188
	ds_read_b128 v[220:223], v176 offset:41472
	ds_read_b128 v[204:207], v188 offset:4608
	ds_read_b128 v[208:211], v188 offset:9216
	ds_read_b128 v[212:215], v187
	s_waitcnt lgkmcnt(4)
	v_mfma_f32_32x32x16_bf16 v[112:127], v[200:203], v[216:219], v[112:127]
	ds_read_b128 v[240:243], v176 offset:36896
	s_waitcnt lgkmcnt(4)
	v_mfma_f32_32x32x16_bf16 v[96:111], v[200:203], v[220:223], v[96:111]
	ds_read_b128 v[224:227], v188 offset:32
	s_waitcnt lgkmcnt(4)
	v_mfma_f32_32x32x16_bf16 v[80:95], v[204:207], v[216:219], v[80:95]
	ds_read_b128 v[244:247], v176 offset:41504
	s_waitcnt lgkmcnt(5)
	v_mfma_f32_32x32x16_bf16 v[64:79], v[204:207], v[220:223], v[64:79]
	ds_read_b128 v[228:231], v188 offset:4640
	s_waitcnt lgkmcnt(5)
	v_mfma_f32_32x32x16_bf16 v[48:63], v[208:211], v[216:219], v[48:63]
	ds_read_b128 v[232:235], v188 offset:9248
	s_waitcnt lgkmcnt(6)
	v_mfma_f32_32x32x16_bf16 v[32:47], v[208:211], v[220:223], v[32:47]
	ds_read_b128 v[236:239], v187 offset:32
	s_waitcnt lgkmcnt(6)
	v_mfma_f32_32x32x16_bf16 v[16:31], v[212:215], v[216:219], v[16:31]
	s_waitcnt lgkmcnt(6)
	v_mfma_f32_32x32x16_bf16 v[0:15], v[212:215], v[220:223], v[0:15]
	s_waitcnt lgkmcnt(4)
	v_mfma_f32_32x32x16_bf16 v[112:127], v[224:227], v[240:243], v[112:127]
	ds_read_b128 v[200:203], v188 offset:64
	s_waitcnt lgkmcnt(4)
	v_mfma_f32_32x32x16_bf16 v[96:111], v[224:227], v[244:247], v[96:111]
	ds_read_b128 v[204:207], v188 offset:4672
	s_waitcnt lgkmcnt(4)
	v_mfma_f32_32x32x16_bf16 v[80:95], v[228:231], v[240:243], v[80:95]
	ds_read_b128 v[208:211], v188 offset:9280
	s_waitcnt lgkmcnt(5)
	v_mfma_f32_32x32x16_bf16 v[64:79], v[228:231], v[244:247], v[64:79]
	ds_read_b128 v[212:215], v187 offset:64
	s_waitcnt lgkmcnt(5)
	v_mfma_f32_32x32x16_bf16 v[48:63], v[232:235], v[240:243], v[48:63]
	ds_read_b128 v[216:219], v176 offset:36928
	s_waitcnt lgkmcnt(6)
	v_mfma_f32_32x32x16_bf16 v[32:47], v[232:235], v[244:247], v[32:47]
	ds_read_b128 v[220:223], v176 offset:41536
	s_waitcnt lgkmcnt(6)
	v_mfma_f32_32x32x16_bf16 v[16:31], v[236:239], v[240:243], v[16:31]
	s_waitcnt lgkmcnt(6)
	v_mfma_f32_32x32x16_bf16 v[0:15], v[236:239], v[244:247], v[0:15]
	s_waitcnt lgkmcnt(1)
	v_mfma_f32_32x32x16_bf16 v[112:127], v[200:203], v[216:219], v[112:127]
	ds_read_b128 v[224:227], v188 offset:96
	s_waitcnt lgkmcnt(1)
	v_mfma_f32_32x32x16_bf16 v[96:111], v[200:203], v[220:223], v[96:111]
	ds_read_b128 v[228:231], v188 offset:4704
	s_waitcnt lgkmcnt(3)
	v_mfma_f32_32x32x16_bf16 v[80:95], v[204:207], v[216:219], v[80:95]
	ds_read_b128 v[232:235], v188 offset:9312
	s_waitcnt lgkmcnt(3)
	v_mfma_f32_32x32x16_bf16 v[64:79], v[204:207], v[220:223], v[64:79]
	ds_read_b128 v[236:239], v187 offset:96
	s_waitcnt lgkmcnt(5)
	v_mfma_f32_32x32x16_bf16 v[48:63], v[208:211], v[216:219], v[48:63]
	ds_read_b128 v[240:243], v176 offset:36960
	s_waitcnt lgkmcnt(5)
	v_mfma_f32_32x32x16_bf16 v[32:47], v[208:211], v[220:223], v[32:47]
	ds_read_b128 v[244:247], v176 offset:41568
	s_waitcnt lgkmcnt(7)
	v_mfma_f32_32x32x16_bf16 v[16:31], v[212:215], v[216:219], v[16:31]
	s_waitcnt lgkmcnt(6)
	v_mfma_f32_32x32x16_bf16 v[0:15], v[212:215], v[220:223], v[0:15]
	s_waitcnt lgkmcnt(1)
	v_mfma_f32_32x32x16_bf16 v[112:127], v[224:227], v[240:243], v[112:127]
	s_waitcnt lgkmcnt(0)
	v_mfma_f32_32x32x16_bf16 v[96:111], v[224:227], v[244:247], v[96:111]
	s_waitcnt lgkmcnt(1)
	v_mfma_f32_32x32x16_bf16 v[80:95], v[228:231], v[240:243], v[80:95]
	s_waitcnt lgkmcnt(0)
	v_mfma_f32_32x32x16_bf16 v[64:79], v[228:231], v[244:247], v[64:79]
	s_waitcnt lgkmcnt(1)
	v_mfma_f32_32x32x16_bf16 v[48:63], v[232:235], v[240:243], v[48:63]
	s_waitcnt lgkmcnt(0)
	v_mfma_f32_32x32x16_bf16 v[32:47], v[232:235], v[244:247], v[32:47]
	s_waitcnt lgkmcnt(1)
	v_mfma_f32_32x32x16_bf16 v[16:31], v[236:239], v[240:243], v[16:31]
	s_waitcnt lgkmcnt(0)
	v_mfma_f32_32x32x16_bf16 v[0:15], v[236:239], v[244:247], v[0:15]
	s_waitcnt vmcnt(0)
	s_mul_i32 s41, s12, 0x1240
	s_add_u32 s42, s30, s41
	s_addc_u32 s43, s31, 0
	s_lshl_b32 s41, s8, 1
	s_add_u32 s42, s42, s41
	s_addc_u32 s43, s43, 0
	s_add_u32 s42, s42, 0x7157900
	s_addc_u32 s43, s43, 0
	v_and_b32_e32 v131, 15, v182
	v_lshrrev_b32_e32 v172, 4, v182
	v_lshl_add_u32 v130, v131, 3, s8
	s_movk_i32 s41, 0x920
	v_cmp_gt_u32_e64 s[44:45], s41, v130
	v_mul_u32_u24_e32 v164, 0x1240, v172
	v_lshl_add_u32 v164, v131, 4, v164
	v_add_u32_e32 v165, 0x12400, v164
	v_add_u32_e32 v166, 0x24800, v164
	v_add_u32_e32 v167, 0x36c00, v164
	v_add_u32_e32 v168, 0x92000, v164
	v_add_u32_e32 v169, 0xa4400, v164
	v_add_u32_e32 v170, 0xb6800, v164
	v_add_u32_e32 v171, 0xc8c00, v164
	v_mul_u32_u24_e32 v129, 0x110, v172
	v_lshl_add_u32 v129, v131, 4, v129
	v_lshrrev_b32_e32 v131, 7, v182
	v_bfe_u32 v172, v182, 5, 1
	v_lshlrev_b32_e32 v131, 6, v131
	v_lshl_or_b32 v131, v172, 2, v131
	v_mul_u32_u24_e32 v131, 136, v131
	v_and_b32_e32 v172, 0x5f, v182
	v_add_lshl_u32 v128, v131, v172, 1
	s_barrier
	v_cvt_pk_bf16_f32 v112, v112, v113
	v_cvt_pk_bf16_f32 v114, v114, v115
	v_cvt_pk_bf16_f32 v116, v116, v117
	v_cvt_pk_bf16_f32 v118, v118, v119
	v_cvt_pk_bf16_f32 v120, v120, v121
	v_cvt_pk_bf16_f32 v122, v122, v123
	v_cvt_pk_bf16_f32 v124, v124, v125
	v_cvt_pk_bf16_f32 v126, v126, v127
	v_cvt_pk_bf16_f32 v96, v96, v97
	v_cvt_pk_bf16_f32 v98, v98, v99
	v_cvt_pk_bf16_f32 v100, v100, v101
	v_cvt_pk_bf16_f32 v102, v102, v103
	v_cvt_pk_bf16_f32 v104, v104, v105
	v_cvt_pk_bf16_f32 v106, v106, v107
	v_cvt_pk_bf16_f32 v108, v108, v109
	v_cvt_pk_bf16_f32 v110, v110, v111
	v_cvt_pk_bf16_f32 v80, v80, v81
	v_cvt_pk_bf16_f32 v82, v82, v83
	v_cvt_pk_bf16_f32 v84, v84, v85
	v_cvt_pk_bf16_f32 v86, v86, v87
	v_cvt_pk_bf16_f32 v88, v88, v89
	v_cvt_pk_bf16_f32 v90, v90, v91
	v_cvt_pk_bf16_f32 v92, v92, v93
	v_cvt_pk_bf16_f32 v94, v94, v95
	v_cvt_pk_bf16_f32 v64, v64, v65
	v_cvt_pk_bf16_f32 v66, v66, v67
	v_cvt_pk_bf16_f32 v68, v68, v69
	v_cvt_pk_bf16_f32 v70, v70, v71
	v_cvt_pk_bf16_f32 v72, v72, v73
	v_cvt_pk_bf16_f32 v74, v74, v75
	v_cvt_pk_bf16_f32 v76, v76, v77
	v_cvt_pk_bf16_f32 v78, v78, v79
	ds_write_b16 v128, v112
	ds_write_b16_d16_hi v128, v112 offset:272
	ds_write_b16 v128, v114 offset:544
	ds_write_b16_d16_hi v128, v114 offset:816
	ds_write_b16 v128, v116 offset:2176
	ds_write_b16_d16_hi v128, v116 offset:2448
	ds_write_b16 v128, v118 offset:2720
	ds_write_b16_d16_hi v128, v118 offset:2992
	ds_write_b16 v128, v120 offset:4352
	ds_write_b16_d16_hi v128, v120 offset:4624
	ds_write_b16 v128, v122 offset:4896
	ds_write_b16_d16_hi v128, v122 offset:5168
	ds_write_b16 v128, v124 offset:6528
	ds_write_b16_d16_hi v128, v124 offset:6800
	ds_write_b16 v128, v126 offset:7072
	ds_write_b16_d16_hi v128, v126 offset:7344
	ds_write_b16 v128, v96 offset:64
	ds_write_b16_d16_hi v128, v96 offset:336
	ds_write_b16 v128, v98 offset:608
	ds_write_b16_d16_hi v128, v98 offset:880
	ds_write_b16 v128, v100 offset:2240
	ds_write_b16_d16_hi v128, v100 offset:2512
	ds_write_b16 v128, v102 offset:2784
	ds_write_b16_d16_hi v128, v102 offset:3056
	ds_write_b16 v128, v104 offset:4416
	ds_write_b16_d16_hi v128, v104 offset:4688
	ds_write_b16 v128, v106 offset:4960
	ds_write_b16_d16_hi v128, v106 offset:5232
	ds_write_b16 v128, v108 offset:6592
	ds_write_b16_d16_hi v128, v108 offset:6864
	ds_write_b16 v128, v110 offset:7136
	ds_write_b16_d16_hi v128, v110 offset:7408
	ds_write_b16 v128, v80 offset:8704
	ds_write_b16_d16_hi v128, v80 offset:8976
	ds_write_b16 v128, v82 offset:9248
	ds_write_b16_d16_hi v128, v82 offset:9520
	ds_write_b16 v128, v84 offset:10880
	ds_write_b16_d16_hi v128, v84 offset:11152
	ds_write_b16 v128, v86 offset:11424
	ds_write_b16_d16_hi v128, v86 offset:11696
	ds_write_b16 v128, v88 offset:13056
	ds_write_b16_d16_hi v128, v88 offset:13328
	ds_write_b16 v128, v90 offset:13600
	ds_write_b16_d16_hi v128, v90 offset:13872
	ds_write_b16 v128, v92 offset:15232
	ds_write_b16_d16_hi v128, v92 offset:15504
	ds_write_b16 v128, v94 offset:15776
	ds_write_b16_d16_hi v128, v94 offset:16048
	ds_write_b16 v128, v64 offset:8768
	ds_write_b16_d16_hi v128, v64 offset:9040
	ds_write_b16 v128, v66 offset:9312
	ds_write_b16_d16_hi v128, v66 offset:9584
	ds_write_b16 v128, v68 offset:10944
	ds_write_b16_d16_hi v128, v68 offset:11216
	ds_write_b16 v128, v70 offset:11488
	ds_write_b16_d16_hi v128, v70 offset:11760
	ds_write_b16 v128, v72 offset:13120
	ds_write_b16_d16_hi v128, v72 offset:13392
	ds_write_b16 v128, v74 offset:13664
	ds_write_b16_d16_hi v128, v74 offset:13936
	ds_write_b16 v128, v76 offset:15296
	ds_write_b16_d16_hi v128, v76 offset:15568
	ds_write_b16 v128, v78 offset:15840
	ds_write_b16_d16_hi v128, v78 offset:16112
	s_waitcnt lgkmcnt(0)
	s_barrier
	ds_read_b128 v[132:135], v129
	ds_read_b128 v[136:139], v129 offset:4352
	ds_read_b128 v[140:143], v129 offset:8704
	ds_read_b128 v[144:147], v129 offset:13056
	ds_read_b128 v[148:151], v129 offset:17408
	ds_read_b128 v[152:155], v129 offset:21760
	ds_read_b128 v[156:159], v129 offset:26112
	ds_read_b128 v[160:163], v129 offset:30464
	v_cvt_pk_bf16_f32 v48, v48, v49
	v_cvt_pk_bf16_f32 v50, v50, v51
	v_cvt_pk_bf16_f32 v52, v52, v53
	v_cvt_pk_bf16_f32 v54, v54, v55
	v_cvt_pk_bf16_f32 v56, v56, v57
	v_cvt_pk_bf16_f32 v58, v58, v59
	v_cvt_pk_bf16_f32 v60, v60, v61
	v_cvt_pk_bf16_f32 v62, v62, v63
	v_cvt_pk_bf16_f32 v32, v32, v33
	v_cvt_pk_bf16_f32 v34, v34, v35
	v_cvt_pk_bf16_f32 v36, v36, v37
	v_cvt_pk_bf16_f32 v38, v38, v39
	v_cvt_pk_bf16_f32 v40, v40, v41
	v_cvt_pk_bf16_f32 v42, v42, v43
	v_cvt_pk_bf16_f32 v44, v44, v45
	v_cvt_pk_bf16_f32 v46, v46, v47
	v_cvt_pk_bf16_f32 v16, v16, v17
	v_cvt_pk_bf16_f32 v18, v18, v19
	v_cvt_pk_bf16_f32 v20, v20, v21
	v_cvt_pk_bf16_f32 v22, v22, v23
	v_cvt_pk_bf16_f32 v24, v24, v25
	v_cvt_pk_bf16_f32 v26, v26, v27
	v_cvt_pk_bf16_f32 v28, v28, v29
	v_cvt_pk_bf16_f32 v30, v30, v31
	v_cvt_pk_bf16_f32 v0, v0, v1
	v_cvt_pk_bf16_f32 v2, v2, v3
	v_cvt_pk_bf16_f32 v4, v4, v5
	v_cvt_pk_bf16_f32 v6, v6, v7
	v_cvt_pk_bf16_f32 v8, v8, v9
	v_cvt_pk_bf16_f32 v10, v10, v11
	v_cvt_pk_bf16_f32 v12, v12, v13
	v_cvt_pk_bf16_f32 v14, v14, v15
	s_and_saveexec_b64 s[46:47], s[44:45]
	s_waitcnt lgkmcnt(7)
	global_store_dwordx4 v164, v[132:135], s[42:43]
	s_waitcnt lgkmcnt(6)
	global_store_dwordx4 v165, v[136:139], s[42:43]
	s_waitcnt lgkmcnt(5)
	global_store_dwordx4 v166, v[140:143], s[42:43]
	s_waitcnt lgkmcnt(4)
	global_store_dwordx4 v167, v[144:147], s[42:43]
	s_waitcnt lgkmcnt(3)
	global_store_dwordx4 v168, v[148:151], s[42:43]
	s_waitcnt lgkmcnt(2)
	global_store_dwordx4 v169, v[152:155], s[42:43]
	s_waitcnt lgkmcnt(1)
	global_store_dwordx4 v170, v[156:159], s[42:43]
	s_waitcnt lgkmcnt(0)
	global_store_dwordx4 v171, v[160:163], s[42:43]
	s_or_b64 exec, exec, s[46:47]
	s_barrier
	ds_write_b16 v128, v48
	ds_write_b16_d16_hi v128, v48 offset:272
	ds_write_b16 v128, v50 offset:544
	ds_write_b16_d16_hi v128, v50 offset:816
	ds_write_b16 v128, v52 offset:2176
	ds_write_b16_d16_hi v128, v52 offset:2448
	ds_write_b16 v128, v54 offset:2720
	ds_write_b16_d16_hi v128, v54 offset:2992
	ds_write_b16 v128, v56 offset:4352
	ds_write_b16_d16_hi v128, v56 offset:4624
	ds_write_b16 v128, v58 offset:4896
	ds_write_b16_d16_hi v128, v58 offset:5168
	ds_write_b16 v128, v60 offset:6528
	ds_write_b16_d16_hi v128, v60 offset:6800
	ds_write_b16 v128, v62 offset:7072
	ds_write_b16_d16_hi v128, v62 offset:7344
	ds_write_b16 v128, v32 offset:64
	ds_write_b16_d16_hi v128, v32 offset:336
	ds_write_b16 v128, v34 offset:608
	ds_write_b16_d16_hi v128, v34 offset:880
	ds_write_b16 v128, v36 offset:2240
	ds_write_b16_d16_hi v128, v36 offset:2512
	ds_write_b16 v128, v38 offset:2784
	ds_write_b16_d16_hi v128, v38 offset:3056
	ds_write_b16 v128, v40 offset:4416
	ds_write_b16_d16_hi v128, v40 offset:4688
	ds_write_b16 v128, v42 offset:4960
	ds_write_b16_d16_hi v128, v42 offset:5232
	ds_write_b16 v128, v44 offset:6592
	ds_write_b16_d16_hi v128, v44 offset:6864
	ds_write_b16 v128, v46 offset:7136
	ds_write_b16_d16_hi v128, v46 offset:7408
	ds_write_b16 v128, v16 offset:8704
	ds_write_b16_d16_hi v128, v16 offset:8976
	ds_write_b16 v128, v18 offset:9248
	ds_write_b16_d16_hi v128, v18 offset:9520
	ds_write_b16 v128, v20 offset:10880
	ds_write_b16_d16_hi v128, v20 offset:11152
	ds_write_b16 v128, v22 offset:11424
	ds_write_b16_d16_hi v128, v22 offset:11696
	ds_write_b16 v128, v24 offset:13056
	ds_write_b16_d16_hi v128, v24 offset:13328
	ds_write_b16 v128, v26 offset:13600
	ds_write_b16_d16_hi v128, v26 offset:13872
	ds_write_b16 v128, v28 offset:15232
	ds_write_b16_d16_hi v128, v28 offset:15504
	ds_write_b16 v128, v30 offset:15776
	ds_write_b16_d16_hi v128, v30 offset:16048
	ds_write_b16 v128, v0 offset:8768
	ds_write_b16_d16_hi v128, v0 offset:9040
	ds_write_b16 v128, v2 offset:9312
	ds_write_b16_d16_hi v128, v2 offset:9584
	ds_write_b16 v128, v4 offset:10944
	ds_write_b16_d16_hi v128, v4 offset:11216
	ds_write_b16 v128, v6 offset:11488
	ds_write_b16_d16_hi v128, v6 offset:11760
	ds_write_b16 v128, v8 offset:13120
	ds_write_b16_d16_hi v128, v8 offset:13392
	ds_write_b16 v128, v10 offset:13664
	ds_write_b16_d16_hi v128, v10 offset:13936
	ds_write_b16 v128, v12 offset:15296
	ds_write_b16_d16_hi v128, v12 offset:15568
	ds_write_b16 v128, v14 offset:15840
	ds_write_b16_d16_hi v128, v14 offset:16112
	s_waitcnt lgkmcnt(0)
	s_barrier
	ds_read_b128 v[132:135], v129
	ds_read_b128 v[136:139], v129 offset:4352
	ds_read_b128 v[140:143], v129 offset:8704
	ds_read_b128 v[144:147], v129 offset:13056
	ds_read_b128 v[148:151], v129 offset:17408
	ds_read_b128 v[152:155], v129 offset:21760
	ds_read_b128 v[156:159], v129 offset:26112
	ds_read_b128 v[160:163], v129 offset:30464
	v_add_u32_e32 v164, 0x49000, v164
	v_add_u32_e32 v165, 0x49000, v165
	v_add_u32_e32 v166, 0x49000, v166
	v_add_u32_e32 v167, 0x49000, v167
	v_add_u32_e32 v168, 0x49000, v168
	v_add_u32_e32 v169, 0x49000, v169
	v_add_u32_e32 v170, 0x49000, v170
	v_add_u32_e32 v171, 0x49000, v171
	s_and_saveexec_b64 s[46:47], s[44:45]
	s_waitcnt lgkmcnt(7)
	global_store_dwordx4 v164, v[132:135], s[42:43]
	s_waitcnt lgkmcnt(6)
	global_store_dwordx4 v165, v[136:139], s[42:43]
	s_waitcnt lgkmcnt(5)
	global_store_dwordx4 v166, v[140:143], s[42:43]
	s_waitcnt lgkmcnt(4)
	global_store_dwordx4 v167, v[144:147], s[42:43]
	s_waitcnt lgkmcnt(3)
	global_store_dwordx4 v168, v[148:151], s[42:43]
	s_waitcnt lgkmcnt(2)
	global_store_dwordx4 v169, v[152:155], s[42:43]
	s_waitcnt lgkmcnt(1)
	global_store_dwordx4 v170, v[156:159], s[42:43]
	s_waitcnt lgkmcnt(0)
	global_store_dwordx4 v171, v[160:163], s[42:43]
	s_or_b64 exec, exec, s[46:47]
	s_branch .LBB0_1281

.LBB0_1977:
	ds_read_b128 v[216:219], v188 offset:36864
	ds_read_b128 v[200:203], v187
	ds_read_b128 v[220:223], v188 offset:41472
	ds_read_b128 v[204:207], v187 offset:4608
	ds_read_b128 v[208:211], v187 offset:9216
	ds_read_b128 v[212:215], v176
	s_waitcnt lgkmcnt(4)
	v_mfma_f32_32x32x16_bf16 v[112:127], v[200:203], v[216:219], v[112:127]
	ds_read_b128 v[240:243], v188 offset:36896
	s_waitcnt lgkmcnt(4)
	v_mfma_f32_32x32x16_bf16 v[96:111], v[200:203], v[220:223], v[96:111]
	ds_read_b128 v[224:227], v187 offset:32
	s_waitcnt lgkmcnt(4)
	v_mfma_f32_32x32x16_bf16 v[80:95], v[204:207], v[216:219], v[80:95]
	ds_read_b128 v[244:247], v188 offset:41504
	s_waitcnt lgkmcnt(5)
	v_mfma_f32_32x32x16_bf16 v[64:79], v[204:207], v[220:223], v[64:79]
	ds_read_b128 v[228:231], v187 offset:4640
	s_waitcnt lgkmcnt(5)
	v_mfma_f32_32x32x16_bf16 v[48:63], v[208:211], v[216:219], v[48:63]
	ds_read_b128 v[232:235], v187 offset:9248
	s_waitcnt lgkmcnt(6)
	v_mfma_f32_32x32x16_bf16 v[32:47], v[208:211], v[220:223], v[32:47]
	ds_read_b128 v[236:239], v176 offset:32
	s_waitcnt lgkmcnt(6)
	v_mfma_f32_32x32x16_bf16 v[16:31], v[212:215], v[216:219], v[16:31]
	s_waitcnt lgkmcnt(6)
	v_mfma_f32_32x32x16_bf16 v[0:15], v[212:215], v[220:223], v[0:15]
	s_waitcnt lgkmcnt(4)
	v_mfma_f32_32x32x16_bf16 v[112:127], v[224:227], v[240:243], v[112:127]
	ds_read_b128 v[200:203], v187 offset:64
	s_waitcnt lgkmcnt(4)
	v_mfma_f32_32x32x16_bf16 v[96:111], v[224:227], v[244:247], v[96:111]
	ds_read_b128 v[204:207], v187 offset:4672
	s_waitcnt lgkmcnt(4)
	v_mfma_f32_32x32x16_bf16 v[80:95], v[228:231], v[240:243], v[80:95]
	ds_read_b128 v[208:211], v187 offset:9280
	s_waitcnt lgkmcnt(5)
	v_mfma_f32_32x32x16_bf16 v[64:79], v[228:231], v[244:247], v[64:79]
	ds_read_b128 v[212:215], v176 offset:64
	s_waitcnt lgkmcnt(5)
	v_mfma_f32_32x32x16_bf16 v[48:63], v[232:235], v[240:243], v[48:63]
	ds_read_b128 v[216:219], v188 offset:36928
	s_waitcnt lgkmcnt(6)
	v_mfma_f32_32x32x16_bf16 v[32:47], v[232:235], v[244:247], v[32:47]
	ds_read_b128 v[220:223], v188 offset:41536
	s_waitcnt lgkmcnt(6)
	v_mfma_f32_32x32x16_bf16 v[16:31], v[236:239], v[240:243], v[16:31]
	s_waitcnt lgkmcnt(6)
	v_mfma_f32_32x32x16_bf16 v[0:15], v[236:239], v[244:247], v[0:15]
	s_waitcnt lgkmcnt(1)
	v_mfma_f32_32x32x16_bf16 v[112:127], v[200:203], v[216:219], v[112:127]
	ds_read_b128 v[224:227], v187 offset:96
	s_waitcnt lgkmcnt(1)
	v_mfma_f32_32x32x16_bf16 v[96:111], v[200:203], v[220:223], v[96:111]
	ds_read_b128 v[228:231], v187 offset:4704
	s_waitcnt lgkmcnt(3)
	v_mfma_f32_32x32x16_bf16 v[80:95], v[204:207], v[216:219], v[80:95]
	ds_read_b128 v[232:235], v187 offset:9312
	s_waitcnt lgkmcnt(3)
	v_mfma_f32_32x32x16_bf16 v[64:79], v[204:207], v[220:223], v[64:79]
	ds_read_b128 v[236:239], v176 offset:96
	s_waitcnt lgkmcnt(5)
	v_mfma_f32_32x32x16_bf16 v[48:63], v[208:211], v[216:219], v[48:63]
	ds_read_b128 v[240:243], v188 offset:36960
	s_waitcnt lgkmcnt(5)
	v_mfma_f32_32x32x16_bf16 v[32:47], v[208:211], v[220:223], v[32:47]
	ds_read_b128 v[244:247], v188 offset:41568
	s_waitcnt lgkmcnt(7)
	v_mfma_f32_32x32x16_bf16 v[16:31], v[212:215], v[216:219], v[16:31]
	s_waitcnt lgkmcnt(6)
	v_mfma_f32_32x32x16_bf16 v[0:15], v[212:215], v[220:223], v[0:15]
	s_waitcnt lgkmcnt(0)
	s_barrier
	s_waitcnt vmcnt(6)
	s_waitcnt lgkmcnt(1)
	v_mfma_f32_32x32x16_bf16 v[112:127], v[224:227], v[240:243], v[112:127]
	ds_write_b128 v189, v[160:163]
	ds_write_b128 v189, v[128:131] offset:4608
	s_waitcnt lgkmcnt(2)
	v_mfma_f32_32x32x16_bf16 v[96:111], v[224:227], v[244:247], v[96:111]
	ds_write_b128 v189, v[132:135] offset:9216
	global_load_dwordx4 v[160:163], v190, s[38:39]
	s_waitcnt lgkmcnt(4)
	v_mfma_f32_32x32x16_bf16 v[80:95], v[228:231], v[240:243], v[80:95]
	ds_write_b128 v189, v[136:139] offset:13824
	ds_write_b128 v189, v[140:143] offset:18432
	global_load_dwordx4 v[128:131], v191, s[38:39]
	s_waitcnt lgkmcnt(5)
	v_mfma_f32_32x32x16_bf16 v[64:79], v[228:231], v[244:247], v[64:79]
	ds_write_b128 v189, v[144:147] offset:23040
	global_load_dwordx4 v[132:135], v192, s[38:39]
	s_waitcnt lgkmcnt(7)
	v_mfma_f32_32x32x16_bf16 v[48:63], v[232:235], v[240:243], v[48:63]
	s_waitcnt vmcnt(8)
	ds_write_b128 v189, v[152:155] offset:36864
	s_waitcnt vmcnt(7)
	ds_write_b128 v189, v[164:167] offset:41472
	global_load_dwordx4 v[136:139], v193, s[38:39]
	s_waitcnt lgkmcnt(8)
	v_mfma_f32_32x32x16_bf16 v[32:47], v[232:235], v[244:247], v[32:47]
	s_waitcnt vmcnt(7)
	ds_write_b128 v189, v[168:171] offset:46080
	global_load_dwordx4 v[140:143], v194, s[38:39]
	s_waitcnt lgkmcnt(10)
	v_mfma_f32_32x32x16_bf16 v[16:31], v[236:239], v[240:243], v[16:31]
	s_waitcnt vmcnt(7)
	ds_write_b128 v189, v[172:175] offset:50688
	s_waitcnt vmcnt(6)
	ds_write_b128 v189, v[148:151] offset:27648
	global_load_dwordx4 v[144:147], v195, s[38:39]
	global_load_dwordx4 v[152:155], v190, s[40:41]
	global_load_dwordx4 v[164:167], v191, s[40:41]
	s_waitcnt lgkmcnt(11)
	v_mfma_f32_32x32x16_bf16 v[0:15], v[236:239], v[244:247], v[0:15]
	s_waitcnt vmcnt(8)
	ds_write_b128 v189, v[156:159] offset:32256
	global_load_dwordx4 v[168:171], v192, s[40:41]
	global_load_dwordx4 v[172:175], v193, s[40:41]
	global_load_dwordx4 v[148:151], v196, s[38:39]
	global_load_dwordx4 v[156:159], v197, s[38:39]
	s_add_u32 s38, s38, 0x80
	s_addc_u32 s39, s39, 0
	s_add_u32 s40, s40, 0x80
	s_addc_u32 s41, s41, 0
	s_add_u32 s12, s12, 0x80
	s_waitcnt lgkmcnt(0)
	s_barrier
	s_cmpk_lg_i32 s12, 0x780
	s_cbranch_scc1 .LBB0_1977
	ds_read_b128 v[216:219], v188 offset:36864
	ds_read_b128 v[200:203], v187
	ds_read_b128 v[220:223], v188 offset:41472
	ds_read_b128 v[204:207], v187 offset:4608
	ds_read_b128 v[208:211], v187 offset:9216
	ds_read_b128 v[212:215], v176
	s_waitcnt lgkmcnt(4)
	v_mfma_f32_32x32x16_bf16 v[112:127], v[200:203], v[216:219], v[112:127]
	ds_read_b128 v[240:243], v188 offset:36896
	s_waitcnt lgkmcnt(4)
	v_mfma_f32_32x32x16_bf16 v[96:111], v[200:203], v[220:223], v[96:111]
	ds_read_b128 v[224:227], v187 offset:32
	s_waitcnt lgkmcnt(4)
	v_mfma_f32_32x32x16_bf16 v[80:95], v[204:207], v[216:219], v[80:95]
	ds_read_b128 v[244:247], v188 offset:41504
	s_waitcnt lgkmcnt(5)
	v_mfma_f32_32x32x16_bf16 v[64:79], v[204:207], v[220:223], v[64:79]
	ds_read_b128 v[228:231], v187 offset:4640
	s_waitcnt lgkmcnt(5)
	v_mfma_f32_32x32x16_bf16 v[48:63], v[208:211], v[216:219], v[48:63]
	ds_read_b128 v[232:235], v187 offset:9248
	s_waitcnt lgkmcnt(6)
	v_mfma_f32_32x32x16_bf16 v[32:47], v[208:211], v[220:223], v[32:47]
	ds_read_b128 v[236:239], v176 offset:32
	s_waitcnt lgkmcnt(6)
	v_mfma_f32_32x32x16_bf16 v[16:31], v[212:215], v[216:219], v[16:31]
	s_waitcnt lgkmcnt(6)
	v_mfma_f32_32x32x16_bf16 v[0:15], v[212:215], v[220:223], v[0:15]
	s_waitcnt lgkmcnt(4)
	v_mfma_f32_32x32x16_bf16 v[112:127], v[224:227], v[240:243], v[112:127]
	ds_read_b128 v[200:203], v187 offset:64
	s_waitcnt lgkmcnt(4)
	v_mfma_f32_32x32x16_bf16 v[96:111], v[224:227], v[244:247], v[96:111]
	ds_read_b128 v[204:207], v187 offset:4672
	s_waitcnt lgkmcnt(4)
	v_mfma_f32_32x32x16_bf16 v[80:95], v[228:231], v[240:243], v[80:95]
	ds_read_b128 v[208:211], v187 offset:9280
	s_waitcnt lgkmcnt(5)
	v_mfma_f32_32x32x16_bf16 v[64:79], v[228:231], v[244:247], v[64:79]
	ds_read_b128 v[212:215], v176 offset:64
	s_waitcnt lgkmcnt(5)
	v_mfma_f32_32x32x16_bf16 v[48:63], v[232:235], v[240:243], v[48:63]
	ds_read_b128 v[216:219], v188 offset:36928
	s_waitcnt lgkmcnt(6)
	v_mfma_f32_32x32x16_bf16 v[32:47], v[232:235], v[244:247], v[32:47]
	ds_read_b128 v[220:223], v188 offset:41536
	s_waitcnt lgkmcnt(6)
	v_mfma_f32_32x32x16_bf16 v[16:31], v[236:239], v[240:243], v[16:31]
	s_waitcnt lgkmcnt(6)
	v_mfma_f32_32x32x16_bf16 v[0:15], v[236:239], v[244:247], v[0:15]
	s_waitcnt lgkmcnt(1)
	v_mfma_f32_32x32x16_bf16 v[112:127], v[200:203], v[216:219], v[112:127]
	ds_read_b128 v[224:227], v187 offset:96
	s_waitcnt lgkmcnt(1)
	v_mfma_f32_32x32x16_bf16 v[96:111], v[200:203], v[220:223], v[96:111]
	ds_read_b128 v[228:231], v187 offset:4704
	s_waitcnt lgkmcnt(3)
	v_mfma_f32_32x32x16_bf16 v[80:95], v[204:207], v[216:219], v[80:95]
	ds_read_b128 v[232:235], v187 offset:9312
	s_waitcnt lgkmcnt(3)
	v_mfma_f32_32x32x16_bf16 v[64:79], v[204:207], v[220:223], v[64:79]
	ds_read_b128 v[236:239], v176 offset:96
	s_waitcnt lgkmcnt(5)
	v_mfma_f32_32x32x16_bf16 v[48:63], v[208:211], v[216:219], v[48:63]
	ds_read_b128 v[240:243], v188 offset:36960
	s_waitcnt lgkmcnt(5)
	v_mfma_f32_32x32x16_bf16 v[32:47], v[208:211], v[220:223], v[32:47]
	ds_read_b128 v[244:247], v188 offset:41568
	s_waitcnt lgkmcnt(7)
	v_mfma_f32_32x32x16_bf16 v[16:31], v[212:215], v[216:219], v[16:31]
	s_waitcnt lgkmcnt(6)
	v_mfma_f32_32x32x16_bf16 v[0:15], v[212:215], v[220:223], v[0:15]
	s_waitcnt lgkmcnt(1)
	v_mfma_f32_32x32x16_bf16 v[112:127], v[224:227], v[240:243], v[112:127]
	s_waitcnt lgkmcnt(0)
	v_mfma_f32_32x32x16_bf16 v[96:111], v[224:227], v[244:247], v[96:111]
	s_waitcnt lgkmcnt(1)
	v_mfma_f32_32x32x16_bf16 v[80:95], v[228:231], v[240:243], v[80:95]
	s_waitcnt lgkmcnt(0)
	v_mfma_f32_32x32x16_bf16 v[64:79], v[228:231], v[244:247], v[64:79]
	s_waitcnt lgkmcnt(1)
	v_mfma_f32_32x32x16_bf16 v[48:63], v[232:235], v[240:243], v[48:63]
	s_waitcnt lgkmcnt(0)
	v_mfma_f32_32x32x16_bf16 v[32:47], v[232:235], v[244:247], v[32:47]
	s_waitcnt lgkmcnt(1)
	v_mfma_f32_32x32x16_bf16 v[16:31], v[236:239], v[240:243], v[16:31]
	s_waitcnt lgkmcnt(0)
	v_mfma_f32_32x32x16_bf16 v[0:15], v[236:239], v[244:247], v[0:15]
	s_waitcnt vmcnt(0)
	s_mul_i32 s42, s6, 0x2000
	s_add_u32 s44, s30, s42
	s_addc_u32 s45, s31, 0
	s_lshl_b32 s42, s58, 1
	s_add_u32 s44, s44, s42
	s_addc_u32 s45, s45, 0
	s_add_u32 s44, s44, 0x7157900
	s_addc_u32 s45, s45, 0
	s_mov_b32 s43, 1
	v_max_f32_e32 v112, 0, v112
	v_max_f32_e32 v113, 0, v113
	v_mul_f32_e32 v112, v112, v112
	v_mul_f32_e32 v113, v113, v113
	v_cvt_pk_bf16_f32 v190, v112, v113
	v_max_f32_e32 v114, 0, v114
	v_max_f32_e32 v115, 0, v115
	v_mul_f32_e32 v114, v114, v114
	v_mul_f32_e32 v115, v115, v115
	v_cvt_pk_bf16_f32 v191, v114, v115
	v_max_f32_e32 v116, 0, v116
	v_max_f32_e32 v117, 0, v117
	v_mul_f32_e32 v116, v116, v116
	v_mul_f32_e32 v117, v117, v117
	v_cvt_pk_bf16_f32 v192, v116, v117
	v_max_f32_e32 v118, 0, v118
	v_max_f32_e32 v119, 0, v119
	v_mul_f32_e32 v118, v118, v118
	v_mul_f32_e32 v119, v119, v119
	v_cvt_pk_bf16_f32 v193, v118, v119
	v_max_f32_e32 v120, 0, v120
	v_max_f32_e32 v121, 0, v121
	v_mul_f32_e32 v120, v120, v120
	v_mul_f32_e32 v121, v121, v121
	v_cvt_pk_bf16_f32 v194, v120, v121
	v_max_f32_e32 v122, 0, v122
	v_max_f32_e32 v123, 0, v123
	v_mul_f32_e32 v122, v122, v122
	v_mul_f32_e32 v123, v123, v123
	v_cvt_pk_bf16_f32 v195, v122, v123
	v_max_f32_e32 v124, 0, v124
	v_max_f32_e32 v125, 0, v125
	v_mul_f32_e32 v124, v124, v124
	v_mul_f32_e32 v125, v125, v125
	v_cvt_pk_bf16_f32 v196, v124, v125
	v_max_f32_e32 v126, 0, v126
	v_max_f32_e32 v127, 0, v127
	v_mul_f32_e32 v126, v126, v126
	v_mul_f32_e32 v127, v127, v127
	v_cvt_pk_bf16_f32 v197, v126, v127
	v_max_f32_e32 v96, 0, v96
	v_max_f32_e32 v97, 0, v97
	v_mul_f32_e32 v96, v96, v96
	v_mul_f32_e32 v97, v97, v97
	v_cvt_pk_bf16_f32 v198, v96, v97
	v_max_f32_e32 v98, 0, v98
	v_max_f32_e32 v99, 0, v99
	v_mul_f32_e32 v98, v98, v98
	v_mul_f32_e32 v99, v99, v99
	v_cvt_pk_bf16_f32 v199, v98, v99
	v_max_f32_e32 v100, 0, v100
	v_max_f32_e32 v101, 0, v101
	v_mul_f32_e32 v100, v100, v100
	v_mul_f32_e32 v101, v101, v101
	v_cvt_pk_bf16_f32 v200, v100, v101
	v_max_f32_e32 v102, 0, v102
	v_max_f32_e32 v103, 0, v103
	v_mul_f32_e32 v102, v102, v102
	v_mul_f32_e32 v103, v103, v103
	v_cvt_pk_bf16_f32 v201, v102, v103
	v_max_f32_e32 v104, 0, v104
	v_max_f32_e32 v105, 0, v105
	v_mul_f32_e32 v104, v104, v104
	v_mul_f32_e32 v105, v105, v105
	v_cvt_pk_bf16_f32 v202, v104, v105
	v_max_f32_e32 v106, 0, v106
	v_max_f32_e32 v107, 0, v107
	v_mul_f32_e32 v106, v106, v106
	v_mul_f32_e32 v107, v107, v107
	v_cvt_pk_bf16_f32 v203, v106, v107
	v_max_f32_e32 v108, 0, v108
	v_max_f32_e32 v109, 0, v109
	v_mul_f32_e32 v108, v108, v108
	v_mul_f32_e32 v109, v109, v109
	v_cvt_pk_bf16_f32 v204, v108, v109
	v_max_f32_e32 v110, 0, v110
	v_max_f32_e32 v111, 0, v111
	v_mul_f32_e32 v110, v110, v110
	v_mul_f32_e32 v111, v111, v111
	v_cvt_pk_bf16_f32 v205, v110, v111
	v_max_f32_e32 v80, 0, v80
	v_max_f32_e32 v81, 0, v81
	v_mul_f32_e32 v80, v80, v80
	v_mul_f32_e32 v81, v81, v81
	v_cvt_pk_bf16_f32 v206, v80, v81
	v_max_f32_e32 v82, 0, v82
	v_max_f32_e32 v83, 0, v83
	v_mul_f32_e32 v82, v82, v82
	v_mul_f32_e32 v83, v83, v83
	v_cvt_pk_bf16_f32 v207, v82, v83
	v_max_f32_e32 v84, 0, v84
	v_max_f32_e32 v85, 0, v85
	v_mul_f32_e32 v84, v84, v84
	v_mul_f32_e32 v85, v85, v85
	v_cvt_pk_bf16_f32 v208, v84, v85
	v_max_f32_e32 v86, 0, v86
	v_max_f32_e32 v87, 0, v87
	v_mul_f32_e32 v86, v86, v86
	v_mul_f32_e32 v87, v87, v87
	v_cvt_pk_bf16_f32 v209, v86, v87
	v_max_f32_e32 v88, 0, v88
	v_max_f32_e32 v89, 0, v89
	v_mul_f32_e32 v88, v88, v88
	v_mul_f32_e32 v89, v89, v89
	v_cvt_pk_bf16_f32 v210, v88, v89
	v_max_f32_e32 v90, 0, v90
	v_max_f32_e32 v91, 0, v91
	v_mul_f32_e32 v90, v90, v90
	v_mul_f32_e32 v91, v91, v91
	v_cvt_pk_bf16_f32 v211, v90, v91
	v_max_f32_e32 v92, 0, v92
	v_max_f32_e32 v93, 0, v93
	v_mul_f32_e32 v92, v92, v92
	v_mul_f32_e32 v93, v93, v93
	v_cvt_pk_bf16_f32 v212, v92, v93
	v_max_f32_e32 v94, 0, v94
	v_max_f32_e32 v95, 0, v95
	v_mul_f32_e32 v94, v94, v94
	v_mul_f32_e32 v95, v95, v95
	v_cvt_pk_bf16_f32 v213, v94, v95
	v_max_f32_e32 v64, 0, v64
	v_max_f32_e32 v65, 0, v65
	v_mul_f32_e32 v64, v64, v64
	v_mul_f32_e32 v65, v65, v65
	v_cvt_pk_bf16_f32 v214, v64, v65
	v_max_f32_e32 v66, 0, v66
	v_max_f32_e32 v67, 0, v67
	v_mul_f32_e32 v66, v66, v66
	v_mul_f32_e32 v67, v67, v67
	v_cvt_pk_bf16_f32 v215, v66, v67
	v_max_f32_e32 v68, 0, v68
	v_max_f32_e32 v69, 0, v69
	v_mul_f32_e32 v68, v68, v68
	v_mul_f32_e32 v69, v69, v69
	v_cvt_pk_bf16_f32 v216, v68, v69
	v_max_f32_e32 v70, 0, v70
	v_max_f32_e32 v71, 0, v71
	v_mul_f32_e32 v70, v70, v70
	v_mul_f32_e32 v71, v71, v71
	v_cvt_pk_bf16_f32 v217, v70, v71
	v_max_f32_e32 v72, 0, v72
	v_max_f32_e32 v73, 0, v73
	v_mul_f32_e32 v72, v72, v72
	v_mul_f32_e32 v73, v73, v73
	v_cvt_pk_bf16_f32 v218, v72, v73
	v_max_f32_e32 v74, 0, v74
	v_max_f32_e32 v75, 0, v75
	v_mul_f32_e32 v74, v74, v74
	v_mul_f32_e32 v75, v75, v75
	v_cvt_pk_bf16_f32 v219, v74, v75
	v_max_f32_e32 v76, 0, v76
	v_max_f32_e32 v77, 0, v77
	v_mul_f32_e32 v76, v76, v76
	v_mul_f32_e32 v77, v77, v77
	v_cvt_pk_bf16_f32 v220, v76, v77
	v_max_f32_e32 v78, 0, v78
	v_max_f32_e32 v79, 0, v79
	v_mul_f32_e32 v78, v78, v78
	v_mul_f32_e32 v79, v79, v79
	v_cvt_pk_bf16_f32 v221, v78, v79
	v_max_f32_e32 v48, 0, v48
	v_max_f32_e32 v49, 0, v49
	v_mul_f32_e32 v48, v48, v48
	v_mul_f32_e32 v49, v49, v49
	v_cvt_pk_bf16_f32 v222, v48, v49
	v_max_f32_e32 v50, 0, v50
	v_max_f32_e32 v51, 0, v51
	v_mul_f32_e32 v50, v50, v50
	v_mul_f32_e32 v51, v51, v51
	v_cvt_pk_bf16_f32 v223, v50, v51
	v_max_f32_e32 v52, 0, v52
	v_max_f32_e32 v53, 0, v53
	v_mul_f32_e32 v52, v52, v52
	v_mul_f32_e32 v53, v53, v53
	v_cvt_pk_bf16_f32 v224, v52, v53
	v_max_f32_e32 v54, 0, v54
	v_max_f32_e32 v55, 0, v55
	v_mul_f32_e32 v54, v54, v54
	v_mul_f32_e32 v55, v55, v55
	v_cvt_pk_bf16_f32 v225, v54, v55
	v_max_f32_e32 v56, 0, v56
	v_max_f32_e32 v57, 0, v57
	v_mul_f32_e32 v56, v56, v56
	v_mul_f32_e32 v57, v57, v57
	v_cvt_pk_bf16_f32 v226, v56, v57
	v_max_f32_e32 v58, 0, v58
	v_max_f32_e32 v59, 0, v59
	v_mul_f32_e32 v58, v58, v58
	v_mul_f32_e32 v59, v59, v59
	v_cvt_pk_bf16_f32 v227, v58, v59
	v_max_f32_e32 v60, 0, v60
	v_max_f32_e32 v61, 0, v61
	v_mul_f32_e32 v60, v60, v60
	v_mul_f32_e32 v61, v61, v61
	v_cvt_pk_bf16_f32 v228, v60, v61
	v_max_f32_e32 v62, 0, v62
	v_max_f32_e32 v63, 0, v63
	v_mul_f32_e32 v62, v62, v62
	v_mul_f32_e32 v63, v63, v63
	v_cvt_pk_bf16_f32 v229, v62, v63
	v_max_f32_e32 v32, 0, v32
	v_max_f32_e32 v33, 0, v33
	v_mul_f32_e32 v32, v32, v32
	v_mul_f32_e32 v33, v33, v33
	v_cvt_pk_bf16_f32 v230, v32, v33
	v_max_f32_e32 v34, 0, v34
	v_max_f32_e32 v35, 0, v35
	v_mul_f32_e32 v34, v34, v34
	v_mul_f32_e32 v35, v35, v35
	v_cvt_pk_bf16_f32 v231, v34, v35
	v_max_f32_e32 v36, 0, v36
	v_max_f32_e32 v37, 0, v37
	v_mul_f32_e32 v36, v36, v36
	v_mul_f32_e32 v37, v37, v37
	v_cvt_pk_bf16_f32 v232, v36, v37
	v_max_f32_e32 v38, 0, v38
	v_max_f32_e32 v39, 0, v39
	v_mul_f32_e32 v38, v38, v38
	v_mul_f32_e32 v39, v39, v39
	v_cvt_pk_bf16_f32 v233, v38, v39
	v_max_f32_e32 v40, 0, v40
	v_max_f32_e32 v41, 0, v41
	v_mul_f32_e32 v40, v40, v40
	v_mul_f32_e32 v41, v41, v41
	v_cvt_pk_bf16_f32 v234, v40, v41
	v_max_f32_e32 v42, 0, v42
	v_max_f32_e32 v43, 0, v43
	v_mul_f32_e32 v42, v42, v42
	v_mul_f32_e32 v43, v43, v43
	v_cvt_pk_bf16_f32 v235, v42, v43
	v_max_f32_e32 v44, 0, v44
	v_max_f32_e32 v45, 0, v45
	v_mul_f32_e32 v44, v44, v44
	v_mul_f32_e32 v45, v45, v45
	v_cvt_pk_bf16_f32 v236, v44, v45
	v_max_f32_e32 v46, 0, v46
	v_max_f32_e32 v47, 0, v47
	v_mul_f32_e32 v46, v46, v46
	v_mul_f32_e32 v47, v47, v47
	v_cvt_pk_bf16_f32 v237, v46, v47
	v_max_f32_e32 v16, 0, v16
	v_max_f32_e32 v17, 0, v17
	v_mul_f32_e32 v16, v16, v16
	v_mul_f32_e32 v17, v17, v17
	v_cvt_pk_bf16_f32 v238, v16, v17
	v_max_f32_e32 v18, 0, v18
	v_max_f32_e32 v19, 0, v19
	v_mul_f32_e32 v18, v18, v18
	v_mul_f32_e32 v19, v19, v19
	v_cvt_pk_bf16_f32 v239, v18, v19
	v_max_f32_e32 v20, 0, v20
	v_max_f32_e32 v21, 0, v21
	v_mul_f32_e32 v20, v20, v20
	v_mul_f32_e32 v21, v21, v21
	v_cvt_pk_bf16_f32 v240, v20, v21
	v_max_f32_e32 v22, 0, v22
	v_max_f32_e32 v23, 0, v23
	v_mul_f32_e32 v22, v22, v22
	v_mul_f32_e32 v23, v23, v23
	v_cvt_pk_bf16_f32 v241, v22, v23
	v_max_f32_e32 v24, 0, v24
	v_max_f32_e32 v25, 0, v25
	v_mul_f32_e32 v24, v24, v24
	v_mul_f32_e32 v25, v25, v25
	v_cvt_pk_bf16_f32 v242, v24, v25
	v_max_f32_e32 v26, 0, v26
	v_max_f32_e32 v27, 0, v27
	v_mul_f32_e32 v26, v26, v26
	v_mul_f32_e32 v27, v27, v27
	v_cvt_pk_bf16_f32 v243, v26, v27
	v_max_f32_e32 v28, 0, v28
	v_max_f32_e32 v29, 0, v29
	v_mul_f32_e32 v28, v28, v28
	v_mul_f32_e32 v29, v29, v29
	v_cvt_pk_bf16_f32 v244, v28, v29
	v_max_f32_e32 v30, 0, v30
	v_max_f32_e32 v31, 0, v31
	v_mul_f32_e32 v30, v30, v30
	v_mul_f32_e32 v31, v31, v31
	v_cvt_pk_bf16_f32 v245, v30, v31
	v_max_f32_e32 v0, 0, v0
	v_max_f32_e32 v1, 0, v1
	v_mul_f32_e32 v0, v0, v0
	v_mul_f32_e32 v1, v1, v1
	v_cvt_pk_bf16_f32 v246, v0, v1
	v_max_f32_e32 v2, 0, v2
	v_max_f32_e32 v3, 0, v3
	v_mul_f32_e32 v2, v2, v2
	v_mul_f32_e32 v3, v3, v3
	v_cvt_pk_bf16_f32 v247, v2, v3
	v_max_f32_e32 v4, 0, v4
	v_max_f32_e32 v5, 0, v5
	v_mul_f32_e32 v4, v4, v4
	v_mul_f32_e32 v5, v5, v5
	v_cvt_pk_bf16_f32 v248, v4, v5
	v_max_f32_e32 v6, 0, v6
	v_max_f32_e32 v7, 0, v7
	v_mul_f32_e32 v6, v6, v6
	v_mul_f32_e32 v7, v7, v7
	v_cvt_pk_bf16_f32 v249, v6, v7
	v_max_f32_e32 v8, 0, v8
	v_max_f32_e32 v9, 0, v9
	v_mul_f32_e32 v8, v8, v8
	v_mul_f32_e32 v9, v9, v9
	v_cvt_pk_bf16_f32 v250, v8, v9
	v_max_f32_e32 v10, 0, v10
	v_max_f32_e32 v11, 0, v11
	v_mul_f32_e32 v10, v10, v10
	v_mul_f32_e32 v11, v11, v11
	v_cvt_pk_bf16_f32 v251, v10, v11
	v_max_f32_e32 v12, 0, v12
	v_max_f32_e32 v13, 0, v13
	v_mul_f32_e32 v12, v12, v12
	v_mul_f32_e32 v13, v13, v13
	v_cvt_pk_bf16_f32 v252, v12, v13
	v_max_f32_e32 v14, 0, v14
	v_max_f32_e32 v15, 0, v15
	v_mul_f32_e32 v14, v14, v14
	v_mul_f32_e32 v15, v15, v15
	v_cvt_pk_bf16_f32 v253, v14, v15
	s_add_i32 s57, s57, s21
	s_add_i32 s56, s56, s21
	s_cmpk_lt_u32 s57, 0x200
	s_cbranch_scc1 .LBB0_1976
	v_and_b32_e32 v3, 15, v182
	v_lshrrev_b32_e32 v4, 4, v182
	v_mul_u32_u24_e32 v2, 0x2000, v4
	v_lshl_add_u32 v2, v3, 4, v2
	v_mul_u32_u24_e32 v1, 0x110, v4
	v_lshl_add_u32 v1, v3, 4, v1
	v_lshrrev_b32_e32 v3, 7, v182
	v_bfe_u32 v4, v182, 5, 1
	v_lshlrev_b32_e32 v3, 6, v3
	v_lshl_or_b32 v3, v4, 2, v3
	v_mul_u32_u24_e32 v3, 136, v3
	v_and_b32_e32 v4, 0x5f, v182
	v_add_lshl_u32 v0, v3, v4, 1
	s_barrier
	ds_write_b16 v0, v190
	ds_write_b16_d16_hi v0, v190 offset:272
	ds_write_b16 v0, v191 offset:544
	ds_write_b16_d16_hi v0, v191 offset:816
	ds_write_b16 v0, v192 offset:2176
	ds_write_b16_d16_hi v0, v192 offset:2448
	ds_write_b16 v0, v193 offset:2720
	ds_write_b16_d16_hi v0, v193 offset:2992
	ds_write_b16 v0, v194 offset:4352
	ds_write_b16_d16_hi v0, v194 offset:4624
	ds_write_b16 v0, v195 offset:4896
	ds_write_b16_d16_hi v0, v195 offset:5168
	ds_write_b16 v0, v196 offset:6528
	ds_write_b16_d16_hi v0, v196 offset:6800
	ds_write_b16 v0, v197 offset:7072
	ds_write_b16_d16_hi v0, v197 offset:7344
	ds_write_b16 v0, v198 offset:64
	ds_write_b16_d16_hi v0, v198 offset:336
	ds_write_b16 v0, v199 offset:608
	ds_write_b16_d16_hi v0, v199 offset:880
	ds_write_b16 v0, v200 offset:2240
	ds_write_b16_d16_hi v0, v200 offset:2512
	ds_write_b16 v0, v201 offset:2784
	ds_write_b16_d16_hi v0, v201 offset:3056
	ds_write_b16 v0, v202 offset:4416
	ds_write_b16_d16_hi v0, v202 offset:4688
	ds_write_b16 v0, v203 offset:4960
	ds_write_b16_d16_hi v0, v203 offset:5232
	ds_write_b16 v0, v204 offset:6592
	ds_write_b16_d16_hi v0, v204 offset:6864
	ds_write_b16 v0, v205 offset:7136
	ds_write_b16_d16_hi v0, v205 offset:7408
	ds_write_b16 v0, v206 offset:8704
	ds_write_b16_d16_hi v0, v206 offset:8976
	ds_write_b16 v0, v207 offset:9248
	ds_write_b16_d16_hi v0, v207 offset:9520
	ds_write_b16 v0, v208 offset:10880
	ds_write_b16_d16_hi v0, v208 offset:11152
	ds_write_b16 v0, v209 offset:11424
	ds_write_b16_d16_hi v0, v209 offset:11696
	ds_write_b16 v0, v210 offset:13056
	ds_write_b16_d16_hi v0, v210 offset:13328
	ds_write_b16 v0, v211 offset:13600
	ds_write_b16_d16_hi v0, v211 offset:13872
	ds_write_b16 v0, v212 offset:15232
	ds_write_b16_d16_hi v0, v212 offset:15504
	ds_write_b16 v0, v213 offset:15776
	ds_write_b16_d16_hi v0, v213 offset:16048
	ds_write_b16 v0, v214 offset:8768
	ds_write_b16_d16_hi v0, v214 offset:9040
	ds_write_b16 v0, v215 offset:9312
	ds_write_b16_d16_hi v0, v215 offset:9584
	ds_write_b16 v0, v216 offset:10944
	ds_write_b16_d16_hi v0, v216 offset:11216
	ds_write_b16 v0, v217 offset:11488
	ds_write_b16_d16_hi v0, v217 offset:11760
	ds_write_b16 v0, v218 offset:13120
	ds_write_b16_d16_hi v0, v218 offset:13392
	ds_write_b16 v0, v219 offset:13664
	ds_write_b16_d16_hi v0, v219 offset:13936
	ds_write_b16 v0, v220 offset:15296
	ds_write_b16_d16_hi v0, v220 offset:15568
	ds_write_b16 v0, v221 offset:15840
	ds_write_b16_d16_hi v0, v221 offset:16112
	s_waitcnt lgkmcnt(0)
	s_barrier
	ds_read_b128 v[8:11], v1
	ds_read_b128 v[12:15], v1 offset:4352
	ds_read_b128 v[16:19], v1 offset:8704
	ds_read_b128 v[20:23], v1 offset:13056
	ds_read_b128 v[24:27], v1 offset:17408
	ds_read_b128 v[28:31], v1 offset:21760
	ds_read_b128 v[32:35], v1 offset:26112
	ds_read_b128 v[36:39], v1 offset:30464
	s_add_u32 s38, s44, 0x0
	s_addc_u32 s39, s45, 0
	s_waitcnt lgkmcnt(7)
	global_store_dwordx4 v2, v[8:11], s[38:39]
	s_add_u32 s38, s44, 0x20000
	s_addc_u32 s39, s45, 0
	s_waitcnt lgkmcnt(6)
	global_store_dwordx4 v2, v[12:15], s[38:39]
	s_add_u32 s38, s44, 0x40000
	s_addc_u32 s39, s45, 0
	s_waitcnt lgkmcnt(5)
	global_store_dwordx4 v2, v[16:19], s[38:39]
	s_add_u32 s38, s44, 0x60000
	s_addc_u32 s39, s45, 0
	s_waitcnt lgkmcnt(4)
	global_store_dwordx4 v2, v[20:23], s[38:39]
	s_add_u32 s38, s44, 0x100000
	s_addc_u32 s39, s45, 0
	s_waitcnt lgkmcnt(3)
	global_store_dwordx4 v2, v[24:27], s[38:39]
	s_add_u32 s38, s44, 0x120000
	s_addc_u32 s39, s45, 0
	s_waitcnt lgkmcnt(2)
	global_store_dwordx4 v2, v[28:31], s[38:39]
	s_add_u32 s38, s44, 0x140000
	s_addc_u32 s39, s45, 0
	s_waitcnt lgkmcnt(1)
	global_store_dwordx4 v2, v[32:35], s[38:39]
	s_add_u32 s38, s44, 0x160000
	s_addc_u32 s39, s45, 0
	s_waitcnt lgkmcnt(0)
	global_store_dwordx4 v2, v[36:39], s[38:39]
	s_barrier
	ds_write_b16 v0, v222
	ds_write_b16_d16_hi v0, v222 offset:272
	ds_write_b16 v0, v223 offset:544
	ds_write_b16_d16_hi v0, v223 offset:816
	ds_write_b16 v0, v224 offset:2176
	ds_write_b16_d16_hi v0, v224 offset:2448
	ds_write_b16 v0, v225 offset:2720
	ds_write_b16_d16_hi v0, v225 offset:2992
	ds_write_b16 v0, v226 offset:4352
	ds_write_b16_d16_hi v0, v226 offset:4624
	ds_write_b16 v0, v227 offset:4896
	ds_write_b16_d16_hi v0, v227 offset:5168
	ds_write_b16 v0, v228 offset:6528
	ds_write_b16_d16_hi v0, v228 offset:6800
	ds_write_b16 v0, v229 offset:7072
	ds_write_b16_d16_hi v0, v229 offset:7344
	ds_write_b16 v0, v230 offset:64
	ds_write_b16_d16_hi v0, v230 offset:336
	ds_write_b16 v0, v231 offset:608
	ds_write_b16_d16_hi v0, v231 offset:880
	ds_write_b16 v0, v232 offset:2240
	ds_write_b16_d16_hi v0, v232 offset:2512
	ds_write_b16 v0, v233 offset:2784
	ds_write_b16_d16_hi v0, v233 offset:3056
	ds_write_b16 v0, v234 offset:4416
	ds_write_b16_d16_hi v0, v234 offset:4688
	ds_write_b16 v0, v235 offset:4960
	ds_write_b16_d16_hi v0, v235 offset:5232
	ds_write_b16 v0, v236 offset:6592
	ds_write_b16_d16_hi v0, v236 offset:6864
	ds_write_b16 v0, v237 offset:7136
	ds_write_b16_d16_hi v0, v237 offset:7408
	ds_write_b16 v0, v238 offset:8704
	ds_write_b16_d16_hi v0, v238 offset:8976
	ds_write_b16 v0, v239 offset:9248
	ds_write_b16_d16_hi v0, v239 offset:9520
	ds_write_b16 v0, v240 offset:10880
	ds_write_b16_d16_hi v0, v240 offset:11152
	ds_write_b16 v0, v241 offset:11424
	ds_write_b16_d16_hi v0, v241 offset:11696
	ds_write_b16 v0, v242 offset:13056
	ds_write_b16_d16_hi v0, v242 offset:13328
	ds_write_b16 v0, v243 offset:13600
	ds_write_b16_d16_hi v0, v243 offset:13872
	ds_write_b16 v0, v244 offset:15232
	ds_write_b16_d16_hi v0, v244 offset:15504
	ds_write_b16 v0, v245 offset:15776
	ds_write_b16_d16_hi v0, v245 offset:16048
	ds_write_b16 v0, v246 offset:8768
	ds_write_b16_d16_hi v0, v246 offset:9040
	ds_write_b16 v0, v247 offset:9312
	ds_write_b16_d16_hi v0, v247 offset:9584
	ds_write_b16 v0, v248 offset:10944
	ds_write_b16_d16_hi v0, v248 offset:11216
	ds_write_b16 v0, v249 offset:11488
	ds_write_b16_d16_hi v0, v249 offset:11760
	ds_write_b16 v0, v250 offset:13120
	ds_write_b16_d16_hi v0, v250 offset:13392
	ds_write_b16 v0, v251 offset:13664
	ds_write_b16_d16_hi v0, v251 offset:13936
	ds_write_b16 v0, v252 offset:15296
	ds_write_b16_d16_hi v0, v252 offset:15568
	ds_write_b16 v0, v253 offset:15840
	ds_write_b16_d16_hi v0, v253 offset:16112
	s_waitcnt lgkmcnt(0)
	s_barrier
	ds_read_b128 v[8:11], v1
	ds_read_b128 v[12:15], v1 offset:4352
	ds_read_b128 v[16:19], v1 offset:8704
	ds_read_b128 v[20:23], v1 offset:13056
	ds_read_b128 v[24:27], v1 offset:17408
	ds_read_b128 v[28:31], v1 offset:21760
	ds_read_b128 v[32:35], v1 offset:26112
	ds_read_b128 v[36:39], v1 offset:30464
	s_add_u32 s38, s44, 0x80000
	s_addc_u32 s39, s45, 0
	s_waitcnt lgkmcnt(7)
	global_store_dwordx4 v2, v[8:11], s[38:39]
	s_add_u32 s38, s44, 0xa0000
	s_addc_u32 s39, s45, 0
	s_waitcnt lgkmcnt(6)
	global_store_dwordx4 v2, v[12:15], s[38:39]
	s_add_u32 s38, s44, 0xc0000
	s_addc_u32 s39, s45, 0
	s_waitcnt lgkmcnt(5)
	global_store_dwordx4 v2, v[16:19], s[38:39]
	s_add_u32 s38, s44, 0xe0000
	s_addc_u32 s39, s45, 0
	s_waitcnt lgkmcnt(4)
	global_store_dwordx4 v2, v[20:23], s[38:39]
	s_add_u32 s38, s44, 0x180000
	s_addc_u32 s39, s45, 0
	s_waitcnt lgkmcnt(3)
	global_store_dwordx4 v2, v[24:27], s[38:39]
	s_add_u32 s38, s44, 0x1a0000
	s_addc_u32 s39, s45, 0
	s_waitcnt lgkmcnt(2)
	global_store_dwordx4 v2, v[28:31], s[38:39]
	s_add_u32 s38, s44, 0x1c0000
	s_addc_u32 s39, s45, 0
	s_waitcnt lgkmcnt(1)
	global_store_dwordx4 v2, v[32:35], s[38:39]
	s_add_u32 s38, s44, 0x1e0000
	s_addc_u32 s39, s45, 0
	s_waitcnt lgkmcnt(0)
	global_store_dwordx4 v2, v[36:39], s[38:39]
	s_mov_b32 s43, 0
	s_branch .LBB0_1969
